# hand-written Proj (w_in) epilogue fast path with 3 straight-line kinds; plus Swiglu fast path, LRU prefetch, sc1 stores, batched epilogue loads
# speedup vs baseline: 1.0267x; 1.0035x over previous
; #define PG8_STAGE(bufoff, gbase, voff) do { _Pragma("unroll") for (int _i = 0; _i < 2; ++_i) \
;         __builtin_amdgcn_global_load_lds((const unsigned*)((const char*)(gbase) + (voff)[_i]), (PG8_LAS unsigned*)(lds + (bufoff) + ldsw + _i * 8192), 16, 0, 0); } while (0)
; #define PG8_LDA(dst, b, h) do { _Pragma("unroll") for (int m = 0; m < 4; ++m) _Pragma("unroll") for (int k = 0; k < 2; ++k) dst[m][k] = *(const PG8_LAS bf16x8*)(lds + PG8_SA(b, h) + aoff + m * 2048 + k * 1024); } while (0)
; #define PG8_LDB(dst, b, h) do { _Pragma("unroll") for (int n = 0; n < 2; ++n) _Pragma("unroll") for (int k = 0; k < 2; ++k) dst[n][k] = *(const PG8_LAS bf16x8*)(lds + PG8_SB(b, h) + boff + n * 2048 + k * 1024); } while (0)
; #define PG8_MMA(ai, bj, At, Bt) do { __builtin_amdgcn_s_setprio(1); _Pragma("unroll") for (int m = 0; m < 4; ++m) _Pragma("unroll") for (int n = 0; n < 2; ++n) _Pragma("unroll") for (int k = 0; k < 2; ++k) \
;         acc[ai][bj][m][n] = __builtin_amdgcn_mfma_f32_16x16x32_bf16(Bt[n][k], At[m][k], acc[ai][bj][m][n], 0, 0, 0); __builtin_amdgcn_s_setprio(0); } while (0)
; #define PG8_WAIT_V(n) asm volatile("s_waitcnt vmcnt(" #n ")" ::: "memory")
; #define PG8_WAIT_L(n) asm volatile("s_waitcnt lgkmcnt(" #n ")" ::: "memory")
; #define PG8_BAR __builtin_amdgcn_s_barrier()
; #define PG8_SCHED __builtin_amdgcn_sched_barrier(0)
; template <class Epi, class Sched, bool ALIGN_EPI = false, bool SP2 = false>
; __device__ __forceinline__ void gemm_phase(PG8_LAS unsigned char* lds, const Gemm g, const Sched& S, const Epi& E) {
;     ...
;             const char* a1 = cA + (size_t)(t + 1) * kstep;
;             const char* a2 = last ? nA : cA + (size_t)(t + 2) * kstep; const char* b2 = last ? nB : cB + (size_t)(t + 2) * kstep;
;             const char* a3 = a2 + kstep; const char* b3 = b2 + kstep;
;             if (last && has_next) S.a_ready(nxt);
;             if constexpr (SP2) {
;             PG8_LDB(B0, 0, 0); PG8_LDB(B1, 0, 1); PG8_SCHED; PG8_LDA(At, 0, 0); PG8_STAGE(PG8_SA(1, 1), a1 + hstep, voffA);
;             PG8_WAIT_V(8); PG8_WAIT_L(0); PG8_BAR; PG8_MMA(0, 0, At, B0); PG8_MMA(0, 1, At, B1); PG8_BAR; PG8_SCHED;
;             PG8_LDA(At, 0, 1); PG8_STAGE(PG8_SB(0, 0), b2, voffB); PG8_STAGE(PG8_SB(0, 1), b2 + hstep, voffB); PG8_STAGE(PG8_SA(0, 0), a2, voffA);
.LBB0_492:
	s_add_u32 s20, s8, 0xfffc0080
	s_addc_u32 s21, s9, -1
	s_add_i32 s48, 0, 0x10000
	s_cmp_eq_u32 s47, 12
	s_cselect_b32 s23, s5, s21
	s_cselect_b32 s22, s7, s20
	v_add_u32_e32 v138, s48, v161
	s_cselect_b32 s21, s13, s46
	s_cselect_b32 s20, s15, s45
	s_add_i32 s50, 0, 0x14000
	ds_read_b128 v[144:147], v138
	ds_read_b128 v[148:151], v138 offset:1024
	ds_read_b128 v[152:155], v138 offset:2048
	ds_read_b128 v[156:159], v138 offset:3072
	v_add_u32_e32 v138, s50, v161
	ds_read_b128 v[166:169], v138
	ds_read_b128 v[170:173], v138 offset:1024
	ds_read_b128 v[174:177], v138 offset:2048
	ds_read_b128 v[178:181], v138 offset:3072
	v_lshl_add_u64 v[138:139], s[8:9], 0, v[136:137]
	s_add_i32 m0, s30, 0xc000
	ds_read_b128 v[182:185], v164
	ds_read_b128 v[186:189], v164 offset:1024
	ds_read_b128 v[190:193], v164 offset:2048
	ds_read_b128 v[194:197], v164 offset:3072
	ds_read_b128 v[198:201], v164 offset:4096
	ds_read_b128 v[202:205], v164 offset:5120
	ds_read_b128 v[224:227], v164 offset:6144
	ds_read_b128 v[228:231], v164 offset:7168
	global_load_lds_dwordx4 v[138:139], off
	v_lshl_add_u64 v[138:139], s[8:9], 0, v[142:143]
	s_add_i32 m0, s30, 0xe000
	s_nop 0
	global_load_lds_dwordx4 v[138:139], off
	s_waitcnt vmcnt(8)
	s_waitcnt lgkmcnt(0)
	s_barrier
	s_setprio 1
	s_waitcnt lgkmcnt(0)
	v_mfma_f32_16x16x32_bf16 v[126:129], v[144:147], v[182:185], v[126:129]
	v_mfma_f32_16x16x32_bf16 v[122:125], v[152:155], v[182:185], v[122:125]
	v_mfma_f32_16x16x32_bf16 v[110:113], v[144:147], v[190:193], v[110:113]
	v_mfma_f32_16x16x32_bf16 v[106:109], v[152:155], v[190:193], v[106:109]
	v_mfma_f32_16x16x32_bf16 v[94:97], v[144:147], v[198:201], v[94:97]
	v_mfma_f32_16x16x32_bf16 v[90:93], v[152:155], v[198:201], v[90:93]
	v_mfma_f32_16x16x32_bf16 v[78:81], v[144:147], v[224:227], v[78:81]
	v_mfma_f32_16x16x32_bf16 v[74:77], v[152:155], v[224:227], v[74:77]
	v_mfma_f32_16x16x32_bf16 v[126:129], v[148:151], v[186:189], v[126:129]
	v_mfma_f32_16x16x32_bf16 v[122:125], v[156:159], v[186:189], v[122:125]
	v_mfma_f32_16x16x32_bf16 v[110:113], v[148:151], v[194:197], v[110:113]
	v_mfma_f32_16x16x32_bf16 v[106:109], v[156:159], v[194:197], v[106:109]
	v_mfma_f32_16x16x32_bf16 v[94:97], v[148:151], v[202:205], v[94:97]
	v_mfma_f32_16x16x32_bf16 v[90:93], v[156:159], v[202:205], v[90:93]
	v_mfma_f32_16x16x32_bf16 v[78:81], v[148:151], v[228:231], v[78:81]
	v_mfma_f32_16x16x32_bf16 v[74:77], v[156:159], v[228:231], v[74:77]
	s_setprio 0
	s_setprio 1
	v_mfma_f32_16x16x32_bf16 v[118:121], v[166:169], v[182:185], v[118:121]
	v_mfma_f32_16x16x32_bf16 v[114:117], v[174:177], v[182:185], v[114:117]
	v_mfma_f32_16x16x32_bf16 v[102:105], v[166:169], v[190:193], v[102:105]
	v_mfma_f32_16x16x32_bf16 v[98:101], v[174:177], v[190:193], v[98:101]
	v_mfma_f32_16x16x32_bf16 v[86:89], v[166:169], v[198:201], v[86:89]
	v_mfma_f32_16x16x32_bf16 v[82:85], v[174:177], v[198:201], v[82:85]
	v_mfma_f32_16x16x32_bf16 v[70:73], v[166:169], v[224:227], v[70:73]
	v_mfma_f32_16x16x32_bf16 v[66:69], v[174:177], v[224:227], v[66:69]
	v_mfma_f32_16x16x32_bf16 v[118:121], v[170:173], v[186:189], v[118:121]
	v_mfma_f32_16x16x32_bf16 v[114:117], v[178:181], v[186:189], v[114:117]
	v_mfma_f32_16x16x32_bf16 v[102:105], v[170:173], v[194:197], v[102:105]
	v_mfma_f32_16x16x32_bf16 v[98:101], v[178:181], v[194:197], v[98:101]
	v_mfma_f32_16x16x32_bf16 v[86:89], v[170:173], v[202:205], v[86:89]
	v_mfma_f32_16x16x32_bf16 v[82:85], v[178:181], v[202:205], v[82:85]
	v_mfma_f32_16x16x32_bf16 v[70:73], v[170:173], v[228:231], v[70:73]
	v_mfma_f32_16x16x32_bf16 v[66:69], v[178:181], v[228:231], v[66:69]
	s_setprio 0
	s_barrier
	s_add_i32 s48, s48, s26
	v_lshl_add_u64 v[138:139], s[20:21], 0, v[0:1]
	s_mov_b32 m0, s48
	ds_read_b128 v[182:185], v164 offset:16384
	ds_read_b128 v[186:189], v164 offset:17408
	ds_read_b128 v[190:193], v164 offset:18432
	ds_read_b128 v[194:197], v164 offset:19456
	ds_read_b128 v[198:201], v164 offset:20480
	ds_read_b128 v[202:205], v164 offset:21504
	ds_read_b128 v[224:227], v164 offset:22528
	ds_read_b128 v[228:231], v164 offset:23552
	global_load_lds_dwordx4 v[138:139], off
	s_add_i32 m0, s48, 0x2000
	s_add_u32 s48, s20, 0x40000
	v_lshl_add_u64 v[140:141], s[20:21], 0, v[134:135]
	s_addc_u32 s49, s21, 0
	s_add_i32 s50, s50, s26
	global_load_lds_dwordx4 v[140:141], off
	v_lshl_add_u64 v[232:233], s[48:49], 0, v[0:1]
	s_mov_b32 m0, s50
	v_lshl_add_u64 v[234:235], s[22:23], 0, v[132:133]
	global_load_lds_dwordx4 v[232:233], off
	v_lshl_add_u64 v[232:233], s[48:49], 0, v[134:135]
	s_add_i32 m0, s50, 0x2000
	s_nop 0
	global_load_lds_dwordx4 v[232:233], off
	v_lshl_add_u64 v[232:233], s[22:23], 0, v[130:131]
	s_mov_b32 m0, s30
	s_nop 0
	global_load_lds_dwordx4 v[232:233], off
	s_mov_b32 m0, s31
	s_nop 0
	global_load_lds_dwordx4 v[234:235], off
	s_waitcnt vmcnt(8)
	s_waitcnt lgkmcnt(0)
	s_barrier
; #define PG8_STAGE(bufoff, gbase, voff) do { _Pragma("unroll") for (int _i = 0; _i < 2; ++_i) \
;         __builtin_amdgcn_global_load_lds((const unsigned*)((const char*)(gbase) + (voff)[_i]), (PG8_LAS unsigned*)(lds + (bufoff) + ldsw + _i * 8192), 16, 0, 0); } while (0)
; #define PG8_LDA(dst, b, h) do { _Pragma("unroll") for (int m = 0; m < 4; ++m) _Pragma("unroll") for (int k = 0; k < 2; ++k) dst[m][k] = *(const PG8_LAS bf16x8*)(lds + PG8_SA(b, h) + aoff + m * 2048 + k * 1024); } while (0)
; #define PG8_LDB(dst, b, h) do { _Pragma("unroll") for (int n = 0; n < 2; ++n) _Pragma("unroll") for (int k = 0; k < 2; ++k) dst[n][k] = *(const PG8_LAS bf16x8*)(lds + PG8_SB(b, h) + boff + n * 2048 + k * 1024); } while (0)
; #define PG8_MMA(ai, bj, At, Bt) do { __builtin_amdgcn_s_setprio(1); _Pragma("unroll") for (int m = 0; m < 4; ++m) _Pragma("unroll") for (int n = 0; n < 2; ++n) _Pragma("unroll") for (int k = 0; k < 2; ++k) \
;         acc[ai][bj][m][n] = __builtin_amdgcn_mfma_f32_16x16x32_bf16(Bt[n][k], At[m][k], acc[ai][bj][m][n], 0, 0, 0); __builtin_amdgcn_s_setprio(0); } while (0)
; #define PG8_WAIT_V(n) asm volatile("s_waitcnt vmcnt(" #n ")" ::: "memory")
; #define PG8_WAIT_L(n) asm volatile("s_waitcnt lgkmcnt(" #n ")" ::: "memory")
; #define PG8_BAR __builtin_amdgcn_s_barrier()
; #define PG8_SCHED __builtin_amdgcn_sched_barrier(0)
; template <class Epi, class Sched, bool ALIGN_EPI = false, bool SP2 = false>
; __device__ __forceinline__ void gemm_phase(PG8_LAS unsigned char* lds, const Gemm g, const Sched& S, const Epi& E) {
;     ...
;             PG8_WAIT_V(8); PG8_WAIT_L(0); PG8_BAR; PG8_MMA(1, 0, At, B0); PG8_MMA(1, 1, At, B1); PG8_BAR; PG8_SCHED;
;             PG8_LDB(B0, 1, 0); PG8_LDB(B1, 1, 1); PG8_SCHED; PG8_LDA(At, 1, 0); PG8_STAGE(PG8_SA(0, 1), a2 + hstep, voffA);
;             PG8_WAIT_V(8); PG8_WAIT_L(0); PG8_BAR; PG8_MMA(0, 0, At, B0); PG8_MMA(0, 1, At, B1); PG8_BAR; PG8_SCHED;
	s_setprio 1
	s_waitcnt lgkmcnt(0)
	v_mfma_f32_16x16x32_bf16 v[62:65], v[144:147], v[182:185], v[62:65]
	v_mfma_f32_16x16x32_bf16 v[58:61], v[152:155], v[182:185], v[58:61]
	v_mfma_f32_16x16x32_bf16 v[46:49], v[144:147], v[190:193], v[46:49]
	v_mfma_f32_16x16x32_bf16 v[42:45], v[152:155], v[190:193], v[42:45]
	v_mfma_f32_16x16x32_bf16 v[30:33], v[144:147], v[198:201], v[30:33]
	v_mfma_f32_16x16x32_bf16 v[26:29], v[152:155], v[198:201], v[26:29]
	v_mfma_f32_16x16x32_bf16 v[14:17], v[144:147], v[224:227], v[14:17]
	v_mfma_f32_16x16x32_bf16 v[10:13], v[152:155], v[224:227], v[10:13]
	v_mfma_f32_16x16x32_bf16 v[62:65], v[148:151], v[186:189], v[62:65]
	v_mfma_f32_16x16x32_bf16 v[58:61], v[156:159], v[186:189], v[58:61]
	v_mfma_f32_16x16x32_bf16 v[46:49], v[148:151], v[194:197], v[46:49]
	v_mfma_f32_16x16x32_bf16 v[42:45], v[156:159], v[194:197], v[42:45]
	v_mfma_f32_16x16x32_bf16 v[30:33], v[148:151], v[202:205], v[30:33]
	v_mfma_f32_16x16x32_bf16 v[26:29], v[156:159], v[202:205], v[26:29]
	v_mfma_f32_16x16x32_bf16 v[14:17], v[148:151], v[228:231], v[14:17]
	v_mfma_f32_16x16x32_bf16 v[10:13], v[156:159], v[228:231], v[10:13]
	s_setprio 0
	s_setprio 1
	v_mfma_f32_16x16x32_bf16 v[54:57], v[166:169], v[182:185], v[54:57]
	v_mfma_f32_16x16x32_bf16 v[50:53], v[174:177], v[182:185], v[50:53]
	v_mfma_f32_16x16x32_bf16 v[38:41], v[166:169], v[190:193], v[38:41]
	v_mfma_f32_16x16x32_bf16 v[34:37], v[174:177], v[190:193], v[34:37]
	v_mfma_f32_16x16x32_bf16 v[22:25], v[166:169], v[198:201], v[22:25]
	v_mfma_f32_16x16x32_bf16 v[18:21], v[174:177], v[198:201], v[18:21]
	v_mfma_f32_16x16x32_bf16 v[6:9], v[166:169], v[224:227], v[6:9]
	v_mfma_f32_16x16x32_bf16 v[2:5], v[174:177], v[224:227], v[2:5]
	v_mfma_f32_16x16x32_bf16 v[54:57], v[170:173], v[186:189], v[54:57]
	v_mfma_f32_16x16x32_bf16 v[50:53], v[178:181], v[186:189], v[50:53]
	v_mfma_f32_16x16x32_bf16 v[38:41], v[170:173], v[194:197], v[38:41]
	v_mfma_f32_16x16x32_bf16 v[34:37], v[178:181], v[194:197], v[34:37]
	v_mfma_f32_16x16x32_bf16 v[22:25], v[170:173], v[202:205], v[22:25]
	v_mfma_f32_16x16x32_bf16 v[18:21], v[178:181], v[202:205], v[18:21]
	v_mfma_f32_16x16x32_bf16 v[6:9], v[170:173], v[228:231], v[6:9]
	v_mfma_f32_16x16x32_bf16 v[2:5], v[178:181], v[228:231], v[2:5]
	s_setprio 0
	s_barrier
	s_add_i32 s48, 0, 0x18000
	s_add_i32 s49, 0, 0x1c000
	v_add_u32_e32 v156, s48, v161
	v_add_u32_e32 v165, s49, v161
	ds_read_b128 v[144:147], v156
	ds_read_b128 v[148:151], v156 offset:1024
	ds_read_b128 v[152:155], v156 offset:2048
	ds_read_b128 v[156:159], v156 offset:3072
	ds_read_b128 v[166:169], v165
	ds_read_b128 v[170:173], v165 offset:1024
	ds_read_b128 v[174:177], v165 offset:2048
	ds_read_b128 v[178:181], v165 offset:3072
	s_add_u32 s22, s22, 0x40000
	s_addc_u32 s23, s23, 0
	s_mov_b32 m0, s38
	v_lshl_add_u64 v[236:237], s[22:23], 0, v[130:131]
	ds_read_b128 v[182:185], v164 offset:32768
	ds_read_b128 v[186:189], v164 offset:33792
	ds_read_b128 v[190:193], v164 offset:34816
	ds_read_b128 v[194:197], v164 offset:35840
	ds_read_b128 v[198:201], v164 offset:36864
	ds_read_b128 v[202:205], v164 offset:37888
	ds_read_b128 v[224:227], v164 offset:38912
	ds_read_b128 v[228:231], v164 offset:39936
	global_load_lds_dwordx4 v[236:237], off
	v_lshl_add_u64 v[236:237], s[22:23], 0, v[132:133]
	s_mov_b32 m0, s39
	s_nop 0
	global_load_lds_dwordx4 v[236:237], off
	s_waitcnt vmcnt(8)
	s_waitcnt lgkmcnt(0)
	s_barrier
	s_setprio 1
	s_waitcnt lgkmcnt(0)
	v_mfma_f32_16x16x32_bf16 v[126:129], v[144:147], v[182:185], v[126:129]
	v_mfma_f32_16x16x32_bf16 v[122:125], v[152:155], v[182:185], v[122:125]
	v_mfma_f32_16x16x32_bf16 v[110:113], v[144:147], v[190:193], v[110:113]
	v_mfma_f32_16x16x32_bf16 v[106:109], v[152:155], v[190:193], v[106:109]
	v_mfma_f32_16x16x32_bf16 v[94:97], v[144:147], v[198:201], v[94:97]
	v_mfma_f32_16x16x32_bf16 v[90:93], v[152:155], v[198:201], v[90:93]
	v_mfma_f32_16x16x32_bf16 v[78:81], v[144:147], v[224:227], v[78:81]
	v_mfma_f32_16x16x32_bf16 v[74:77], v[152:155], v[224:227], v[74:77]
	v_mfma_f32_16x16x32_bf16 v[126:129], v[148:151], v[186:189], v[126:129]
	v_mfma_f32_16x16x32_bf16 v[122:125], v[156:159], v[186:189], v[122:125]
	v_mfma_f32_16x16x32_bf16 v[110:113], v[148:151], v[194:197], v[110:113]
	v_mfma_f32_16x16x32_bf16 v[106:109], v[156:159], v[194:197], v[106:109]
	v_mfma_f32_16x16x32_bf16 v[94:97], v[148:151], v[202:205], v[94:97]
	v_mfma_f32_16x16x32_bf16 v[90:93], v[156:159], v[202:205], v[90:93]
	v_mfma_f32_16x16x32_bf16 v[78:81], v[148:151], v[228:231], v[78:81]
	v_mfma_f32_16x16x32_bf16 v[74:77], v[156:159], v[228:231], v[74:77]
	s_setprio 0
	s_setprio 1
	v_mfma_f32_16x16x32_bf16 v[118:121], v[166:169], v[182:185], v[118:121]
	v_mfma_f32_16x16x32_bf16 v[114:117], v[174:177], v[182:185], v[114:117]
	v_mfma_f32_16x16x32_bf16 v[102:105], v[166:169], v[190:193], v[102:105]
	v_mfma_f32_16x16x32_bf16 v[98:101], v[174:177], v[190:193], v[98:101]
	v_mfma_f32_16x16x32_bf16 v[86:89], v[166:169], v[198:201], v[86:89]
	v_mfma_f32_16x16x32_bf16 v[82:85], v[174:177], v[198:201], v[82:85]
	v_mfma_f32_16x16x32_bf16 v[70:73], v[166:169], v[224:227], v[70:73]
	v_mfma_f32_16x16x32_bf16 v[66:69], v[174:177], v[224:227], v[66:69]
	v_mfma_f32_16x16x32_bf16 v[118:121], v[170:173], v[186:189], v[118:121]
	v_mfma_f32_16x16x32_bf16 v[114:117], v[178:181], v[186:189], v[114:117]
	v_mfma_f32_16x16x32_bf16 v[102:105], v[170:173], v[194:197], v[102:105]
	v_mfma_f32_16x16x32_bf16 v[98:101], v[178:181], v[194:197], v[98:101]
	v_mfma_f32_16x16x32_bf16 v[86:89], v[170:173], v[202:205], v[86:89]
	v_mfma_f32_16x16x32_bf16 v[82:85], v[178:181], v[202:205], v[82:85]
	v_mfma_f32_16x16x32_bf16 v[70:73], v[170:173], v[228:231], v[70:73]
	v_mfma_f32_16x16x32_bf16 v[66:69], v[178:181], v[228:231], v[66:69]
	s_setprio 0
	s_barrier
; #define PG8_STAGE(bufoff, gbase, voff) do { _Pragma("unroll") for (int _i = 0; _i < 2; ++_i) \
;         __builtin_amdgcn_global_load_lds((const unsigned*)((const char*)(gbase) + (voff)[_i]), (PG8_LAS unsigned*)(lds + (bufoff) + ldsw + _i * 8192), 16, 0, 0); } while (0)
; #define PG8_LDA(dst, b, h) do { _Pragma("unroll") for (int m = 0; m < 4; ++m) _Pragma("unroll") for (int k = 0; k < 2; ++k) dst[m][k] = *(const PG8_LAS bf16x8*)(lds + PG8_SA(b, h) + aoff + m * 2048 + k * 1024); } while (0)
; #define PG8_MMA(ai, bj, At, Bt) do { __builtin_amdgcn_s_setprio(1); _Pragma("unroll") for (int m = 0; m < 4; ++m) _Pragma("unroll") for (int n = 0; n < 2; ++n) _Pragma("unroll") for (int k = 0; k < 2; ++k) \
;         acc[ai][bj][m][n] = __builtin_amdgcn_mfma_f32_16x16x32_bf16(Bt[n][k], At[m][k], acc[ai][bj][m][n], 0, 0, 0); __builtin_amdgcn_s_setprio(0); } while (0)
; #define PG8_WAIT_V(n) asm volatile("s_waitcnt vmcnt(" #n ")" ::: "memory")
; #define PG8_WAIT_L(n) asm volatile("s_waitcnt lgkmcnt(" #n ")" ::: "memory")
; #define PG8_BAR __builtin_amdgcn_s_barrier()
; #define PG8_SCHED __builtin_amdgcn_sched_barrier(0)
; template <class Epi, class Sched, bool ALIGN_EPI = false, bool SP2 = false>
; __device__ __forceinline__ void gemm_phase(PG8_LAS unsigned char* lds, const Gemm g, const Sched& S, const Epi& E) {
;     ...
;             PG8_LDA(At, 1, 1); PG8_STAGE(PG8_SB(1, 0), b3, voffB); PG8_STAGE(PG8_SB(1, 1), b3 + hstep, voffB); PG8_STAGE(PG8_SA(1, 0), a3, voffA);
;             PG8_WAIT_V(8); PG8_WAIT_L(0); PG8_BAR; PG8_MMA(1, 0, At, B0); PG8_MMA(1, 1, At, B1); PG8_BAR; PG8_SCHED;
;     __device__ __forceinline__ void operator()(const f32x4 (&acc)[2][2][4][2], const Unit& u, int wr, int wc, int fr, int fq) const {
;         const int row0 = u.pm * 256 + wr * 64 + fr; const int kind = u.pn < 7 ? 0 : (u.pn < 12 ? 1 : 2);
;         bf16_t* base = kind == 0 ? P1 : P2; const int ld = kind == 0 ? P1W : P2W; const int col0 = (kind == 0 ? u.pn : u.pn - 7) * 256 + wc * 32 + 8 * fq;
;         const float c3 = kind == 1 ? -LOG2E_ * 1.5957691216f * 0.044715f : 0.f, c1 = kind == 1 ? -LOG2E_ * 1.5957691216f : -LOG2E_;
; #pragma unroll
;         for (int ai = 0; ai < 2; ++ai)
; #pragma unroll
;             for (int m = 0; m < 4; ++m) {
;                 const int row = row0 + ai * 128 + m * 16; const float rs = (u.pm == pm0) ? RS[row & 255] : row_rstd(ss, row);
	s_add_i32 s22, s48, s26
	v_lshl_add_u64 v[138:139], v[138:139], 0, s[86:87]
	s_mov_b32 m0, s22
	ds_read_b128 v[182:185], v164 offset:49152
	ds_read_b128 v[186:189], v164 offset:50176
	ds_read_b128 v[190:193], v164 offset:51200
	ds_read_b128 v[194:197], v164 offset:52224
	ds_read_b128 v[198:201], v164 offset:53248
	ds_read_b128 v[202:205], v164 offset:54272
	ds_read_b128 v[224:227], v164 offset:55296
	ds_read_b128 v[228:231], v164 offset:56320
	global_load_lds_dwordx4 v[138:139], off
	s_add_i32 m0, s22, 0x2000
	s_add_u32 s20, s20, 0x40080
	v_lshl_add_u64 v[138:139], v[140:141], 0, s[86:87]
	s_addc_u32 s21, s21, 0
	s_add_i32 s22, s49, s26
	global_load_lds_dwordx4 v[138:139], off
	v_lshl_add_u64 v[138:139], s[20:21], 0, v[0:1]
	s_mov_b32 m0, s22
	s_nop 0
	global_load_lds_dwordx4 v[138:139], off
	v_lshl_add_u64 v[138:139], s[20:21], 0, v[134:135]
	s_add_i32 m0, s22, 0x2000
	s_nop 0
	global_load_lds_dwordx4 v[138:139], off
	v_lshl_add_u64 v[138:139], v[232:233], 0, s[86:87]
	s_mov_b32 m0, s41
	s_nop 0
	global_load_lds_dwordx4 v[138:139], off
	v_lshl_add_u64 v[138:139], v[234:235], 0, s[86:87]
	s_mov_b32 m0, s42
	s_nop 0
	global_load_lds_dwordx4 v[138:139], off
	s_waitcnt vmcnt(8)
	s_waitcnt lgkmcnt(0)
	s_barrier
	s_setprio 1
	s_waitcnt lgkmcnt(0)
	v_mfma_f32_16x16x32_bf16 v[62:65], v[144:147], v[182:185], v[62:65]
	v_mfma_f32_16x16x32_bf16 v[58:61], v[152:155], v[182:185], v[58:61]
	v_mfma_f32_16x16x32_bf16 v[46:49], v[144:147], v[190:193], v[46:49]
	v_mfma_f32_16x16x32_bf16 v[42:45], v[152:155], v[190:193], v[42:45]
	v_mfma_f32_16x16x32_bf16 v[30:33], v[144:147], v[198:201], v[30:33]
	v_mfma_f32_16x16x32_bf16 v[26:29], v[152:155], v[198:201], v[26:29]
	v_mfma_f32_16x16x32_bf16 v[14:17], v[144:147], v[224:227], v[14:17]
	v_mfma_f32_16x16x32_bf16 v[10:13], v[152:155], v[224:227], v[10:13]
	v_mfma_f32_16x16x32_bf16 v[62:65], v[148:151], v[186:189], v[62:65]
	v_mfma_f32_16x16x32_bf16 v[58:61], v[156:159], v[186:189], v[58:61]
	v_mfma_f32_16x16x32_bf16 v[46:49], v[148:151], v[194:197], v[46:49]
	v_mfma_f32_16x16x32_bf16 v[42:45], v[156:159], v[194:197], v[42:45]
	v_mfma_f32_16x16x32_bf16 v[30:33], v[148:151], v[202:205], v[30:33]
	v_mfma_f32_16x16x32_bf16 v[26:29], v[156:159], v[202:205], v[26:29]
	v_mfma_f32_16x16x32_bf16 v[14:17], v[148:151], v[228:231], v[14:17]
	v_mfma_f32_16x16x32_bf16 v[10:13], v[156:159], v[228:231], v[10:13]
	s_setprio 0
	s_setprio 1
	v_mfma_f32_16x16x32_bf16 v[54:57], v[166:169], v[182:185], v[54:57]
	v_mfma_f32_16x16x32_bf16 v[50:53], v[174:177], v[182:185], v[50:53]
	v_mfma_f32_16x16x32_bf16 v[38:41], v[166:169], v[190:193], v[38:41]
	v_mfma_f32_16x16x32_bf16 v[34:37], v[174:177], v[190:193], v[34:37]
	v_mfma_f32_16x16x32_bf16 v[22:25], v[166:169], v[198:201], v[22:25]
	v_mfma_f32_16x16x32_bf16 v[18:21], v[174:177], v[198:201], v[18:21]
	v_mfma_f32_16x16x32_bf16 v[6:9], v[166:169], v[224:227], v[6:9]
	v_mfma_f32_16x16x32_bf16 v[2:5], v[174:177], v[224:227], v[2:5]
	v_mfma_f32_16x16x32_bf16 v[54:57], v[170:173], v[186:189], v[54:57]
	v_mfma_f32_16x16x32_bf16 v[50:53], v[178:181], v[186:189], v[50:53]
	v_mfma_f32_16x16x32_bf16 v[38:41], v[170:173], v[194:197], v[38:41]
	v_mfma_f32_16x16x32_bf16 v[34:37], v[178:181], v[194:197], v[34:37]
	v_mfma_f32_16x16x32_bf16 v[22:25], v[170:173], v[202:205], v[22:25]
	v_mfma_f32_16x16x32_bf16 v[18:21], v[178:181], v[202:205], v[18:21]
	v_mfma_f32_16x16x32_bf16 v[6:9], v[170:173], v[228:231], v[6:9]
	v_mfma_f32_16x16x32_bf16 v[2:5], v[178:181], v[228:231], v[2:5]
	s_setprio 0
	s_barrier
	s_add_i32 s47, s47, 2
	s_add_u32 s8, s8, 0x100
	s_addc_u32 s9, s9, 0
	s_add_u32 s45, s45, 0x100
	s_addc_u32 s46, s46, 0
	s_cmp_gt_u32 s47, 13
	s_cbranch_scc0 .LBB0_492
	ds_read_b32 v224, v162
	ds_read_b32 v225, v162 offset:64
	ds_read_b32 v226, v162 offset:128
	ds_read_b32 v227, v162 offset:192
	ds_read_b32 v228, v162 offset:512
	ds_read_b32 v229, v162 offset:576
	ds_read_b32 v230, v162 offset:640
	ds_read_b32 v231, v162 offset:704
	s_and_b64 vcc, exec, s[10:11]
	s_cbranch_vccz .LBB0_495
	s_barrier
.LBB0_495:
	s_cmp_lg_u32 s4, s24
	s_cbranch_scc1 .Lpj_slow
	v_lshl_add_u32 v140, s4, 8, v160
	s_cmp_lt_i32 s6, 7
	s_cbranch_scc1 .Lpj_k0
	s_cmp_lt_i32 s6, 12
	s_cbranch_scc1 .Lpj_k1
	s_add_i32 s13, s6, -7
	s_lshl_b32 s13, s13, 8
	v_or_b32_e32 v141, s13, v163
	v_mul_u32_u24_e32 v140, 0x1a00, v140
	v_lshl_add_u32 v140, v141, 1, v140
	v_mov_b32_e32 v146, 0xbfb8aa3b
	v_mov_b32_e32 v147, 0xbfb8aa3b
	s_waitcnt lgkmcnt(7)
; __device__ __forceinline__ u32x4 pack8(const f32x4 a, const f32x4 b) { u32x4 w; w.x = cvt_pk_bf16(a[0], a[1]); w.y = cvt_pk_bf16(a[2], a[3]); w.z = cvt_pk_bf16(b[0], b[1]); w.w = cvt_pk_bf16(b[2], b[3]); return w; }
;     __device__ __forceinline__ void operator()(const f32x4 (&acc)[2][2][4][2], const Unit& u, int wr, int wc, int fr, int fq) const {
;     ...
;                 const int row = row0 + ai * 128 + m * 16; const float rs = (u.pm == pm0) ? RS[row & 255] : row_rstd(ss, row);
; #pragma unroll
;                 for (int bj = 0; bj < 2; ++bj) {
;                     f32x4 v[2], e[2];
; #pragma unroll
;                     for (int n = 0; n < 2; ++n) { v[n] = acc[ai][bj][m][n] * rs; e[n] = v[n] * ((v[n] * v[n]) * c3 + c1); }
;                     if (kind != 0) {
; #pragma unroll
;                         for (int n = 0; n < 2; ++n)
; #pragma unroll
;                             for (int j = 0; j < 4; ++j) e[n][j] = __builtin_amdgcn_exp2f(e[n][j]);
; #pragma unroll
;                         for (int n = 0; n < 2; ++n) e[n] = e[n] + 1.0f;
; #pragma unroll
;                         for (int n = 0; n < 2; ++n)
; #pragma unroll
;                             for (int j = 0; j < 4; ++j) e[n][j] = __builtin_amdgcn_rcpf(e[n][j]);
;                         if (kind == 1) { v[0] = v[0] * e[0]; v[1] = v[1] * e[1]; } else { v[0] = e[0]; v[1] = e[1]; }
;                     }
;                     __builtin_nontemporal_store(pack8(v[0], v[1]), (u32x4*)(base + (size_t)row * ld + col0 + bj * 128));
	v_mov_b32_e32 v138, v224
	v_pk_mul_f32 v[126:127], v[126:127], v[138:139] op_sel_hi:[1,0]
	v_pk_mul_f32 v[128:129], v[128:129], v[138:139] op_sel_hi:[1,0]
	v_pk_mul_f32 v[122:123], v[122:123], v[138:139] op_sel_hi:[1,0]
	v_pk_mul_f32 v[124:125], v[124:125], v[138:139] op_sel_hi:[1,0]
	v_pk_mul_f32 v[166:167], v[126:127], v[146:147]
	v_pk_mul_f32 v[168:169], v[128:129], v[146:147]
	v_pk_mul_f32 v[170:171], v[122:123], v[146:147]
	v_pk_mul_f32 v[172:173], v[124:125], v[146:147]
	v_exp_f32_e32 v166, v166
	v_exp_f32_e32 v167, v167
	v_exp_f32_e32 v168, v168
	v_exp_f32_e32 v169, v169
	v_exp_f32_e32 v170, v170
	v_exp_f32_e32 v171, v171
	v_exp_f32_e32 v172, v172
	v_exp_f32_e32 v173, v173
	v_pk_add_f32 v[166:167], v[166:167], 1.0 op_sel_hi:[1,0]
	v_pk_add_f32 v[168:169], v[168:169], 1.0 op_sel_hi:[1,0]
	v_pk_add_f32 v[170:171], v[170:171], 1.0 op_sel_hi:[1,0]
	v_pk_add_f32 v[172:173], v[172:173], 1.0 op_sel_hi:[1,0]
	v_rcp_f32_e32 v166, v166
	v_rcp_f32_e32 v167, v167
	v_rcp_f32_e32 v168, v168
	v_rcp_f32_e32 v169, v169
	v_rcp_f32_e32 v170, v170
	v_rcp_f32_e32 v171, v171
	v_rcp_f32_e32 v172, v172
	v_rcp_f32_e32 v173, v173
	v_cvt_pk_bf16_f32 v126, v166, v167
	v_cvt_pk_bf16_f32 v127, v168, v169
	v_cvt_pk_bf16_f32 v128, v170, v171
	v_cvt_pk_bf16_f32 v129, v172, v173
	global_store_dwordx4 v140, v[126:129], s[56:57] sc1
	v_pk_mul_f32 v[118:119], v[118:119], v[138:139] op_sel_hi:[1,0]
	v_pk_mul_f32 v[120:121], v[120:121], v[138:139] op_sel_hi:[1,0]
	v_pk_mul_f32 v[114:115], v[114:115], v[138:139] op_sel_hi:[1,0]
	v_pk_mul_f32 v[116:117], v[116:117], v[138:139] op_sel_hi:[1,0]
	v_pk_mul_f32 v[166:167], v[118:119], v[146:147]
	v_pk_mul_f32 v[168:169], v[120:121], v[146:147]
	v_pk_mul_f32 v[170:171], v[114:115], v[146:147]
	v_pk_mul_f32 v[172:173], v[116:117], v[146:147]
	v_exp_f32_e32 v166, v166
	v_exp_f32_e32 v167, v167
	v_exp_f32_e32 v168, v168
	v_exp_f32_e32 v169, v169
	v_exp_f32_e32 v170, v170
	v_exp_f32_e32 v171, v171
	v_exp_f32_e32 v172, v172
	v_exp_f32_e32 v173, v173
	v_pk_add_f32 v[166:167], v[166:167], 1.0 op_sel_hi:[1,0]
	v_pk_add_f32 v[168:169], v[168:169], 1.0 op_sel_hi:[1,0]
	v_pk_add_f32 v[170:171], v[170:171], 1.0 op_sel_hi:[1,0]
	v_pk_add_f32 v[172:173], v[172:173], 1.0 op_sel_hi:[1,0]
	v_rcp_f32_e32 v166, v166
	v_rcp_f32_e32 v167, v167
	v_rcp_f32_e32 v168, v168
	v_rcp_f32_e32 v169, v169
	v_rcp_f32_e32 v170, v170
	v_rcp_f32_e32 v171, v171
	v_rcp_f32_e32 v172, v172
	v_rcp_f32_e32 v173, v173
	v_cvt_pk_bf16_f32 v118, v166, v167
	v_cvt_pk_bf16_f32 v119, v168, v169
	v_cvt_pk_bf16_f32 v120, v170, v171
	v_cvt_pk_bf16_f32 v121, v172, v173
	global_store_dwordx4 v140, v[118:121], s[56:57] offset:256 sc1
	s_waitcnt lgkmcnt(6)
	v_mov_b32_e32 v138, v225
	v_add_u32_e32 v141, 0x1a000, v140
	v_pk_mul_f32 v[110:111], v[110:111], v[138:139] op_sel_hi:[1,0]
	v_pk_mul_f32 v[112:113], v[112:113], v[138:139] op_sel_hi:[1,0]
	v_pk_mul_f32 v[106:107], v[106:107], v[138:139] op_sel_hi:[1,0]
	v_pk_mul_f32 v[108:109], v[108:109], v[138:139] op_sel_hi:[1,0]
	v_pk_mul_f32 v[166:167], v[110:111], v[146:147]
	v_pk_mul_f32 v[168:169], v[112:113], v[146:147]
	v_pk_mul_f32 v[170:171], v[106:107], v[146:147]
	v_pk_mul_f32 v[172:173], v[108:109], v[146:147]
	v_exp_f32_e32 v166, v166
	v_exp_f32_e32 v167, v167
	v_exp_f32_e32 v168, v168
	v_exp_f32_e32 v169, v169
	v_exp_f32_e32 v170, v170
	v_exp_f32_e32 v171, v171
	v_exp_f32_e32 v172, v172
	v_exp_f32_e32 v173, v173
	v_pk_add_f32 v[166:167], v[166:167], 1.0 op_sel_hi:[1,0]
	v_pk_add_f32 v[168:169], v[168:169], 1.0 op_sel_hi:[1,0]
	v_pk_add_f32 v[170:171], v[170:171], 1.0 op_sel_hi:[1,0]
	v_pk_add_f32 v[172:173], v[172:173], 1.0 op_sel_hi:[1,0]
	v_rcp_f32_e32 v166, v166
	v_rcp_f32_e32 v167, v167
	v_rcp_f32_e32 v168, v168
	v_rcp_f32_e32 v169, v169
	v_rcp_f32_e32 v170, v170
	v_rcp_f32_e32 v171, v171
	v_rcp_f32_e32 v172, v172
	v_rcp_f32_e32 v173, v173
	v_cvt_pk_bf16_f32 v110, v166, v167
	v_cvt_pk_bf16_f32 v111, v168, v169
	v_cvt_pk_bf16_f32 v112, v170, v171
	v_cvt_pk_bf16_f32 v113, v172, v173
	global_store_dwordx4 v141, v[110:113], s[56:57] sc1
	v_pk_mul_f32 v[102:103], v[102:103], v[138:139] op_sel_hi:[1,0]
	v_pk_mul_f32 v[104:105], v[104:105], v[138:139] op_sel_hi:[1,0]
	v_pk_mul_f32 v[98:99], v[98:99], v[138:139] op_sel_hi:[1,0]
	v_pk_mul_f32 v[100:101], v[100:101], v[138:139] op_sel_hi:[1,0]
	v_pk_mul_f32 v[166:167], v[102:103], v[146:147]
	v_pk_mul_f32 v[168:169], v[104:105], v[146:147]
	v_pk_mul_f32 v[170:171], v[98:99], v[146:147]
	v_pk_mul_f32 v[172:173], v[100:101], v[146:147]
	v_exp_f32_e32 v166, v166
	v_exp_f32_e32 v167, v167
	v_exp_f32_e32 v168, v168
	v_exp_f32_e32 v169, v169
	v_exp_f32_e32 v170, v170
	v_exp_f32_e32 v171, v171
	v_exp_f32_e32 v172, v172
	v_exp_f32_e32 v173, v173
	v_pk_add_f32 v[166:167], v[166:167], 1.0 op_sel_hi:[1,0]
	v_pk_add_f32 v[168:169], v[168:169], 1.0 op_sel_hi:[1,0]
	v_pk_add_f32 v[170:171], v[170:171], 1.0 op_sel_hi:[1,0]
	v_pk_add_f32 v[172:173], v[172:173], 1.0 op_sel_hi:[1,0]
	v_rcp_f32_e32 v166, v166
	v_rcp_f32_e32 v167, v167
	v_rcp_f32_e32 v168, v168
	v_rcp_f32_e32 v169, v169
	v_rcp_f32_e32 v170, v170
	v_rcp_f32_e32 v171, v171
	v_rcp_f32_e32 v172, v172
	v_rcp_f32_e32 v173, v173
	v_cvt_pk_bf16_f32 v102, v166, v167
	v_cvt_pk_bf16_f32 v103, v168, v169
	v_cvt_pk_bf16_f32 v104, v170, v171
	v_cvt_pk_bf16_f32 v105, v172, v173
	global_store_dwordx4 v141, v[102:105], s[56:57] offset:256 sc1
	s_waitcnt lgkmcnt(5)
; __device__ __forceinline__ u32x4 pack8(const f32x4 a, const f32x4 b) { u32x4 w; w.x = cvt_pk_bf16(a[0], a[1]); w.y = cvt_pk_bf16(a[2], a[3]); w.z = cvt_pk_bf16(b[0], b[1]); w.w = cvt_pk_bf16(b[2], b[3]); return w; }
;     __device__ __forceinline__ void operator()(const f32x4 (&acc)[2][2][4][2], const Unit& u, int wr, int wc, int fr, int fq) const {
;     ...
;                 const int row = row0 + ai * 128 + m * 16; const float rs = (u.pm == pm0) ? RS[row & 255] : row_rstd(ss, row);
; #pragma unroll
;                 for (int bj = 0; bj < 2; ++bj) {
;                     f32x4 v[2], e[2];
; #pragma unroll
;                     for (int n = 0; n < 2; ++n) { v[n] = acc[ai][bj][m][n] * rs; e[n] = v[n] * ((v[n] * v[n]) * c3 + c1); }
;                     if (kind != 0) {
; #pragma unroll
;                         for (int n = 0; n < 2; ++n)
; #pragma unroll
;                             for (int j = 0; j < 4; ++j) e[n][j] = __builtin_amdgcn_exp2f(e[n][j]);
; #pragma unroll
;                         for (int n = 0; n < 2; ++n) e[n] = e[n] + 1.0f;
; #pragma unroll
;                         for (int n = 0; n < 2; ++n)
; #pragma unroll
;                             for (int j = 0; j < 4; ++j) e[n][j] = __builtin_amdgcn_rcpf(e[n][j]);
;                         if (kind == 1) { v[0] = v[0] * e[0]; v[1] = v[1] * e[1]; } else { v[0] = e[0]; v[1] = e[1]; }
;                     }
;                     __builtin_nontemporal_store(pack8(v[0], v[1]), (u32x4*)(base + (size_t)row * ld + col0 + bj * 128));
	v_mov_b32_e32 v138, v226
	v_add_u32_e32 v141, 0x34000, v140
	v_pk_mul_f32 v[94:95], v[94:95], v[138:139] op_sel_hi:[1,0]
	v_pk_mul_f32 v[96:97], v[96:97], v[138:139] op_sel_hi:[1,0]
	v_pk_mul_f32 v[90:91], v[90:91], v[138:139] op_sel_hi:[1,0]
	v_pk_mul_f32 v[92:93], v[92:93], v[138:139] op_sel_hi:[1,0]
	v_pk_mul_f32 v[166:167], v[94:95], v[146:147]
	v_pk_mul_f32 v[168:169], v[96:97], v[146:147]
	v_pk_mul_f32 v[170:171], v[90:91], v[146:147]
	v_pk_mul_f32 v[172:173], v[92:93], v[146:147]
	v_exp_f32_e32 v166, v166
	v_exp_f32_e32 v167, v167
	v_exp_f32_e32 v168, v168
	v_exp_f32_e32 v169, v169
	v_exp_f32_e32 v170, v170
	v_exp_f32_e32 v171, v171
	v_exp_f32_e32 v172, v172
	v_exp_f32_e32 v173, v173
	v_pk_add_f32 v[166:167], v[166:167], 1.0 op_sel_hi:[1,0]
	v_pk_add_f32 v[168:169], v[168:169], 1.0 op_sel_hi:[1,0]
	v_pk_add_f32 v[170:171], v[170:171], 1.0 op_sel_hi:[1,0]
	v_pk_add_f32 v[172:173], v[172:173], 1.0 op_sel_hi:[1,0]
	v_rcp_f32_e32 v166, v166
	v_rcp_f32_e32 v167, v167
	v_rcp_f32_e32 v168, v168
	v_rcp_f32_e32 v169, v169
	v_rcp_f32_e32 v170, v170
	v_rcp_f32_e32 v171, v171
	v_rcp_f32_e32 v172, v172
	v_rcp_f32_e32 v173, v173
	v_cvt_pk_bf16_f32 v94, v166, v167
	v_cvt_pk_bf16_f32 v95, v168, v169
	v_cvt_pk_bf16_f32 v96, v170, v171
	v_cvt_pk_bf16_f32 v97, v172, v173
	global_store_dwordx4 v141, v[94:97], s[56:57] sc1
	v_pk_mul_f32 v[86:87], v[86:87], v[138:139] op_sel_hi:[1,0]
	v_pk_mul_f32 v[88:89], v[88:89], v[138:139] op_sel_hi:[1,0]
	v_pk_mul_f32 v[82:83], v[82:83], v[138:139] op_sel_hi:[1,0]
	v_pk_mul_f32 v[84:85], v[84:85], v[138:139] op_sel_hi:[1,0]
	v_pk_mul_f32 v[166:167], v[86:87], v[146:147]
	v_pk_mul_f32 v[168:169], v[88:89], v[146:147]
	v_pk_mul_f32 v[170:171], v[82:83], v[146:147]
	v_pk_mul_f32 v[172:173], v[84:85], v[146:147]
	v_exp_f32_e32 v166, v166
	v_exp_f32_e32 v167, v167
	v_exp_f32_e32 v168, v168
	v_exp_f32_e32 v169, v169
	v_exp_f32_e32 v170, v170
	v_exp_f32_e32 v171, v171
	v_exp_f32_e32 v172, v172
	v_exp_f32_e32 v173, v173
	v_pk_add_f32 v[166:167], v[166:167], 1.0 op_sel_hi:[1,0]
	v_pk_add_f32 v[168:169], v[168:169], 1.0 op_sel_hi:[1,0]
	v_pk_add_f32 v[170:171], v[170:171], 1.0 op_sel_hi:[1,0]
	v_pk_add_f32 v[172:173], v[172:173], 1.0 op_sel_hi:[1,0]
	v_rcp_f32_e32 v166, v166
	v_rcp_f32_e32 v167, v167
	v_rcp_f32_e32 v168, v168
	v_rcp_f32_e32 v169, v169
	v_rcp_f32_e32 v170, v170
	v_rcp_f32_e32 v171, v171
	v_rcp_f32_e32 v172, v172
	v_rcp_f32_e32 v173, v173
	v_cvt_pk_bf16_f32 v86, v166, v167
	v_cvt_pk_bf16_f32 v87, v168, v169
	v_cvt_pk_bf16_f32 v88, v170, v171
	v_cvt_pk_bf16_f32 v89, v172, v173
	global_store_dwordx4 v141, v[86:89], s[56:57] offset:256 sc1
	s_waitcnt lgkmcnt(4)
	v_mov_b32_e32 v138, v227
	v_add_u32_e32 v141, 0x4e000, v140
	v_pk_mul_f32 v[78:79], v[78:79], v[138:139] op_sel_hi:[1,0]
	v_pk_mul_f32 v[80:81], v[80:81], v[138:139] op_sel_hi:[1,0]
	v_pk_mul_f32 v[74:75], v[74:75], v[138:139] op_sel_hi:[1,0]
	v_pk_mul_f32 v[76:77], v[76:77], v[138:139] op_sel_hi:[1,0]
	v_pk_mul_f32 v[166:167], v[78:79], v[146:147]
	v_pk_mul_f32 v[168:169], v[80:81], v[146:147]
	v_pk_mul_f32 v[170:171], v[74:75], v[146:147]
	v_pk_mul_f32 v[172:173], v[76:77], v[146:147]
	v_exp_f32_e32 v166, v166
	v_exp_f32_e32 v167, v167
	v_exp_f32_e32 v168, v168
	v_exp_f32_e32 v169, v169
	v_exp_f32_e32 v170, v170
	v_exp_f32_e32 v171, v171
	v_exp_f32_e32 v172, v172
	v_exp_f32_e32 v173, v173
	v_pk_add_f32 v[166:167], v[166:167], 1.0 op_sel_hi:[1,0]
	v_pk_add_f32 v[168:169], v[168:169], 1.0 op_sel_hi:[1,0]
	v_pk_add_f32 v[170:171], v[170:171], 1.0 op_sel_hi:[1,0]
	v_pk_add_f32 v[172:173], v[172:173], 1.0 op_sel_hi:[1,0]
	v_rcp_f32_e32 v166, v166
	v_rcp_f32_e32 v167, v167
	v_rcp_f32_e32 v168, v168
	v_rcp_f32_e32 v169, v169
	v_rcp_f32_e32 v170, v170
	v_rcp_f32_e32 v171, v171
	v_rcp_f32_e32 v172, v172
	v_rcp_f32_e32 v173, v173
	v_cvt_pk_bf16_f32 v78, v166, v167
	v_cvt_pk_bf16_f32 v79, v168, v169
	v_cvt_pk_bf16_f32 v80, v170, v171
	v_cvt_pk_bf16_f32 v81, v172, v173
	global_store_dwordx4 v141, v[78:81], s[56:57] sc1
	v_pk_mul_f32 v[70:71], v[70:71], v[138:139] op_sel_hi:[1,0]
	v_pk_mul_f32 v[72:73], v[72:73], v[138:139] op_sel_hi:[1,0]
	v_pk_mul_f32 v[66:67], v[66:67], v[138:139] op_sel_hi:[1,0]
	v_pk_mul_f32 v[68:69], v[68:69], v[138:139] op_sel_hi:[1,0]
	v_pk_mul_f32 v[166:167], v[70:71], v[146:147]
	v_pk_mul_f32 v[168:169], v[72:73], v[146:147]
	v_pk_mul_f32 v[170:171], v[66:67], v[146:147]
	v_pk_mul_f32 v[172:173], v[68:69], v[146:147]
	v_exp_f32_e32 v166, v166
	v_exp_f32_e32 v167, v167
	v_exp_f32_e32 v168, v168
	v_exp_f32_e32 v169, v169
	v_exp_f32_e32 v170, v170
	v_exp_f32_e32 v171, v171
	v_exp_f32_e32 v172, v172
	v_exp_f32_e32 v173, v173
	v_pk_add_f32 v[166:167], v[166:167], 1.0 op_sel_hi:[1,0]
	v_pk_add_f32 v[168:169], v[168:169], 1.0 op_sel_hi:[1,0]
	v_pk_add_f32 v[170:171], v[170:171], 1.0 op_sel_hi:[1,0]
	v_pk_add_f32 v[172:173], v[172:173], 1.0 op_sel_hi:[1,0]
	v_rcp_f32_e32 v166, v166
	v_rcp_f32_e32 v167, v167
	v_rcp_f32_e32 v168, v168
	v_rcp_f32_e32 v169, v169
	v_rcp_f32_e32 v170, v170
	v_rcp_f32_e32 v171, v171
	v_rcp_f32_e32 v172, v172
	v_rcp_f32_e32 v173, v173
	v_cvt_pk_bf16_f32 v70, v166, v167
	v_cvt_pk_bf16_f32 v71, v168, v169
	v_cvt_pk_bf16_f32 v72, v170, v171
	v_cvt_pk_bf16_f32 v73, v172, v173
	global_store_dwordx4 v141, v[70:73], s[56:57] offset:256 sc1
	s_waitcnt lgkmcnt(3)
; __device__ __forceinline__ u32x4 pack8(const f32x4 a, const f32x4 b) { u32x4 w; w.x = cvt_pk_bf16(a[0], a[1]); w.y = cvt_pk_bf16(a[2], a[3]); w.z = cvt_pk_bf16(b[0], b[1]); w.w = cvt_pk_bf16(b[2], b[3]); return w; }
;     __device__ __forceinline__ void operator()(const f32x4 (&acc)[2][2][4][2], const Unit& u, int wr, int wc, int fr, int fq) const {
;     ...
;                 const int row = row0 + ai * 128 + m * 16; const float rs = (u.pm == pm0) ? RS[row & 255] : row_rstd(ss, row);
; #pragma unroll
;                 for (int bj = 0; bj < 2; ++bj) {
;                     f32x4 v[2], e[2];
; #pragma unroll
;                     for (int n = 0; n < 2; ++n) { v[n] = acc[ai][bj][m][n] * rs; e[n] = v[n] * ((v[n] * v[n]) * c3 + c1); }
;                     if (kind != 0) {
; #pragma unroll
;                         for (int n = 0; n < 2; ++n)
; #pragma unroll
;                             for (int j = 0; j < 4; ++j) e[n][j] = __builtin_amdgcn_exp2f(e[n][j]);
; #pragma unroll
;                         for (int n = 0; n < 2; ++n) e[n] = e[n] + 1.0f;
; #pragma unroll
;                         for (int n = 0; n < 2; ++n)
; #pragma unroll
;                             for (int j = 0; j < 4; ++j) e[n][j] = __builtin_amdgcn_rcpf(e[n][j]);
;                         if (kind == 1) { v[0] = v[0] * e[0]; v[1] = v[1] * e[1]; } else { v[0] = e[0]; v[1] = e[1]; }
;                     }
;                     __builtin_nontemporal_store(pack8(v[0], v[1]), (u32x4*)(base + (size_t)row * ld + col0 + bj * 128));
	v_mov_b32_e32 v138, v228
	v_add_u32_e32 v141, 0xd0000, v140
	v_pk_mul_f32 v[62:63], v[62:63], v[138:139] op_sel_hi:[1,0]
	v_pk_mul_f32 v[64:65], v[64:65], v[138:139] op_sel_hi:[1,0]
	v_pk_mul_f32 v[58:59], v[58:59], v[138:139] op_sel_hi:[1,0]
	v_pk_mul_f32 v[60:61], v[60:61], v[138:139] op_sel_hi:[1,0]
	v_pk_mul_f32 v[166:167], v[62:63], v[146:147]
	v_pk_mul_f32 v[168:169], v[64:65], v[146:147]
	v_pk_mul_f32 v[170:171], v[58:59], v[146:147]
	v_pk_mul_f32 v[172:173], v[60:61], v[146:147]
	v_exp_f32_e32 v166, v166
	v_exp_f32_e32 v167, v167
	v_exp_f32_e32 v168, v168
	v_exp_f32_e32 v169, v169
	v_exp_f32_e32 v170, v170
	v_exp_f32_e32 v171, v171
	v_exp_f32_e32 v172, v172
	v_exp_f32_e32 v173, v173
	v_pk_add_f32 v[166:167], v[166:167], 1.0 op_sel_hi:[1,0]
	v_pk_add_f32 v[168:169], v[168:169], 1.0 op_sel_hi:[1,0]
	v_pk_add_f32 v[170:171], v[170:171], 1.0 op_sel_hi:[1,0]
	v_pk_add_f32 v[172:173], v[172:173], 1.0 op_sel_hi:[1,0]
	v_rcp_f32_e32 v166, v166
	v_rcp_f32_e32 v167, v167
	v_rcp_f32_e32 v168, v168
	v_rcp_f32_e32 v169, v169
	v_rcp_f32_e32 v170, v170
	v_rcp_f32_e32 v171, v171
	v_rcp_f32_e32 v172, v172
	v_rcp_f32_e32 v173, v173
	v_cvt_pk_bf16_f32 v62, v166, v167
	v_cvt_pk_bf16_f32 v63, v168, v169
	v_cvt_pk_bf16_f32 v64, v170, v171
	v_cvt_pk_bf16_f32 v65, v172, v173
	global_store_dwordx4 v141, v[62:65], s[56:57] sc1
	v_pk_mul_f32 v[54:55], v[54:55], v[138:139] op_sel_hi:[1,0]
	v_pk_mul_f32 v[56:57], v[56:57], v[138:139] op_sel_hi:[1,0]
	v_pk_mul_f32 v[50:51], v[50:51], v[138:139] op_sel_hi:[1,0]
	v_pk_mul_f32 v[52:53], v[52:53], v[138:139] op_sel_hi:[1,0]
	v_pk_mul_f32 v[166:167], v[54:55], v[146:147]
	v_pk_mul_f32 v[168:169], v[56:57], v[146:147]
	v_pk_mul_f32 v[170:171], v[50:51], v[146:147]
	v_pk_mul_f32 v[172:173], v[52:53], v[146:147]
	v_exp_f32_e32 v166, v166
	v_exp_f32_e32 v167, v167
	v_exp_f32_e32 v168, v168
	v_exp_f32_e32 v169, v169
	v_exp_f32_e32 v170, v170
	v_exp_f32_e32 v171, v171
	v_exp_f32_e32 v172, v172
	v_exp_f32_e32 v173, v173
	v_pk_add_f32 v[166:167], v[166:167], 1.0 op_sel_hi:[1,0]
	v_pk_add_f32 v[168:169], v[168:169], 1.0 op_sel_hi:[1,0]
	v_pk_add_f32 v[170:171], v[170:171], 1.0 op_sel_hi:[1,0]
	v_pk_add_f32 v[172:173], v[172:173], 1.0 op_sel_hi:[1,0]
	v_rcp_f32_e32 v166, v166
	v_rcp_f32_e32 v167, v167
	v_rcp_f32_e32 v168, v168
	v_rcp_f32_e32 v169, v169
	v_rcp_f32_e32 v170, v170
	v_rcp_f32_e32 v171, v171
	v_rcp_f32_e32 v172, v172
	v_rcp_f32_e32 v173, v173
	v_cvt_pk_bf16_f32 v54, v166, v167
	v_cvt_pk_bf16_f32 v55, v168, v169
	v_cvt_pk_bf16_f32 v56, v170, v171
	v_cvt_pk_bf16_f32 v57, v172, v173
	global_store_dwordx4 v141, v[54:57], s[56:57] offset:256 sc1
	s_waitcnt lgkmcnt(2)
	v_mov_b32_e32 v138, v229
	v_add_u32_e32 v141, 0xea000, v140
	v_pk_mul_f32 v[46:47], v[46:47], v[138:139] op_sel_hi:[1,0]
	v_pk_mul_f32 v[48:49], v[48:49], v[138:139] op_sel_hi:[1,0]
	v_pk_mul_f32 v[42:43], v[42:43], v[138:139] op_sel_hi:[1,0]
	v_pk_mul_f32 v[44:45], v[44:45], v[138:139] op_sel_hi:[1,0]
	v_pk_mul_f32 v[166:167], v[46:47], v[146:147]
	v_pk_mul_f32 v[168:169], v[48:49], v[146:147]
	v_pk_mul_f32 v[170:171], v[42:43], v[146:147]
	v_pk_mul_f32 v[172:173], v[44:45], v[146:147]
	v_exp_f32_e32 v166, v166
	v_exp_f32_e32 v167, v167
	v_exp_f32_e32 v168, v168
	v_exp_f32_e32 v169, v169
	v_exp_f32_e32 v170, v170
	v_exp_f32_e32 v171, v171
	v_exp_f32_e32 v172, v172
	v_exp_f32_e32 v173, v173
	v_pk_add_f32 v[166:167], v[166:167], 1.0 op_sel_hi:[1,0]
	v_pk_add_f32 v[168:169], v[168:169], 1.0 op_sel_hi:[1,0]
	v_pk_add_f32 v[170:171], v[170:171], 1.0 op_sel_hi:[1,0]
	v_pk_add_f32 v[172:173], v[172:173], 1.0 op_sel_hi:[1,0]
	v_rcp_f32_e32 v166, v166
	v_rcp_f32_e32 v167, v167
	v_rcp_f32_e32 v168, v168
	v_rcp_f32_e32 v169, v169
	v_rcp_f32_e32 v170, v170
	v_rcp_f32_e32 v171, v171
	v_rcp_f32_e32 v172, v172
	v_rcp_f32_e32 v173, v173
	v_cvt_pk_bf16_f32 v46, v166, v167
	v_cvt_pk_bf16_f32 v47, v168, v169
	v_cvt_pk_bf16_f32 v48, v170, v171
	v_cvt_pk_bf16_f32 v49, v172, v173
	global_store_dwordx4 v141, v[46:49], s[56:57] sc1
	v_pk_mul_f32 v[38:39], v[38:39], v[138:139] op_sel_hi:[1,0]
	v_pk_mul_f32 v[40:41], v[40:41], v[138:139] op_sel_hi:[1,0]
	v_pk_mul_f32 v[34:35], v[34:35], v[138:139] op_sel_hi:[1,0]
	v_pk_mul_f32 v[36:37], v[36:37], v[138:139] op_sel_hi:[1,0]
	v_pk_mul_f32 v[166:167], v[38:39], v[146:147]
	v_pk_mul_f32 v[168:169], v[40:41], v[146:147]
	v_pk_mul_f32 v[170:171], v[34:35], v[146:147]
	v_pk_mul_f32 v[172:173], v[36:37], v[146:147]
	v_exp_f32_e32 v166, v166
	v_exp_f32_e32 v167, v167
	v_exp_f32_e32 v168, v168
	v_exp_f32_e32 v169, v169
	v_exp_f32_e32 v170, v170
	v_exp_f32_e32 v171, v171
	v_exp_f32_e32 v172, v172
	v_exp_f32_e32 v173, v173
	v_pk_add_f32 v[166:167], v[166:167], 1.0 op_sel_hi:[1,0]
	v_pk_add_f32 v[168:169], v[168:169], 1.0 op_sel_hi:[1,0]
	v_pk_add_f32 v[170:171], v[170:171], 1.0 op_sel_hi:[1,0]
	v_pk_add_f32 v[172:173], v[172:173], 1.0 op_sel_hi:[1,0]
	v_rcp_f32_e32 v166, v166
	v_rcp_f32_e32 v167, v167
	v_rcp_f32_e32 v168, v168
	v_rcp_f32_e32 v169, v169
	v_rcp_f32_e32 v170, v170
	v_rcp_f32_e32 v171, v171
	v_rcp_f32_e32 v172, v172
	v_rcp_f32_e32 v173, v173
	v_cvt_pk_bf16_f32 v38, v166, v167
	v_cvt_pk_bf16_f32 v39, v168, v169
	v_cvt_pk_bf16_f32 v40, v170, v171
	v_cvt_pk_bf16_f32 v41, v172, v173
	global_store_dwordx4 v141, v[38:41], s[56:57] offset:256 sc1
	s_waitcnt lgkmcnt(1)
; __device__ __forceinline__ u32x4 pack8(const f32x4 a, const f32x4 b) { u32x4 w; w.x = cvt_pk_bf16(a[0], a[1]); w.y = cvt_pk_bf16(a[2], a[3]); w.z = cvt_pk_bf16(b[0], b[1]); w.w = cvt_pk_bf16(b[2], b[3]); return w; }
;     __device__ __forceinline__ void operator()(const f32x4 (&acc)[2][2][4][2], const Unit& u, int wr, int wc, int fr, int fq) const {
;     ...
;                 const int row = row0 + ai * 128 + m * 16; const float rs = (u.pm == pm0) ? RS[row & 255] : row_rstd(ss, row);
; #pragma unroll
;                 for (int bj = 0; bj < 2; ++bj) {
;                     f32x4 v[2], e[2];
; #pragma unroll
;                     for (int n = 0; n < 2; ++n) { v[n] = acc[ai][bj][m][n] * rs; e[n] = v[n] * ((v[n] * v[n]) * c3 + c1); }
;                     if (kind != 0) {
; #pragma unroll
;                         for (int n = 0; n < 2; ++n)
; #pragma unroll
;                             for (int j = 0; j < 4; ++j) e[n][j] = __builtin_amdgcn_exp2f(e[n][j]);
; #pragma unroll
;                         for (int n = 0; n < 2; ++n) e[n] = e[n] + 1.0f;
; #pragma unroll
;                         for (int n = 0; n < 2; ++n)
; #pragma unroll
;                             for (int j = 0; j < 4; ++j) e[n][j] = __builtin_amdgcn_rcpf(e[n][j]);
;                         if (kind == 1) { v[0] = v[0] * e[0]; v[1] = v[1] * e[1]; } else { v[0] = e[0]; v[1] = e[1]; }
;                     }
;                     __builtin_nontemporal_store(pack8(v[0], v[1]), (u32x4*)(base + (size_t)row * ld + col0 + bj * 128));
	v_mov_b32_e32 v138, v230
	v_add_u32_e32 v141, 0x104000, v140
	v_pk_mul_f32 v[30:31], v[30:31], v[138:139] op_sel_hi:[1,0]
	v_pk_mul_f32 v[32:33], v[32:33], v[138:139] op_sel_hi:[1,0]
	v_pk_mul_f32 v[26:27], v[26:27], v[138:139] op_sel_hi:[1,0]
	v_pk_mul_f32 v[28:29], v[28:29], v[138:139] op_sel_hi:[1,0]
	v_pk_mul_f32 v[166:167], v[30:31], v[146:147]
	v_pk_mul_f32 v[168:169], v[32:33], v[146:147]
	v_pk_mul_f32 v[170:171], v[26:27], v[146:147]
	v_pk_mul_f32 v[172:173], v[28:29], v[146:147]
	v_exp_f32_e32 v166, v166
	v_exp_f32_e32 v167, v167
	v_exp_f32_e32 v168, v168
	v_exp_f32_e32 v169, v169
	v_exp_f32_e32 v170, v170
	v_exp_f32_e32 v171, v171
	v_exp_f32_e32 v172, v172
	v_exp_f32_e32 v173, v173
	v_pk_add_f32 v[166:167], v[166:167], 1.0 op_sel_hi:[1,0]
	v_pk_add_f32 v[168:169], v[168:169], 1.0 op_sel_hi:[1,0]
	v_pk_add_f32 v[170:171], v[170:171], 1.0 op_sel_hi:[1,0]
	v_pk_add_f32 v[172:173], v[172:173], 1.0 op_sel_hi:[1,0]
	v_rcp_f32_e32 v166, v166
	v_rcp_f32_e32 v167, v167
	v_rcp_f32_e32 v168, v168
	v_rcp_f32_e32 v169, v169
	v_rcp_f32_e32 v170, v170
	v_rcp_f32_e32 v171, v171
	v_rcp_f32_e32 v172, v172
	v_rcp_f32_e32 v173, v173
	v_cvt_pk_bf16_f32 v30, v166, v167
	v_cvt_pk_bf16_f32 v31, v168, v169
	v_cvt_pk_bf16_f32 v32, v170, v171
	v_cvt_pk_bf16_f32 v33, v172, v173
	global_store_dwordx4 v141, v[30:33], s[56:57] sc1
	v_pk_mul_f32 v[22:23], v[22:23], v[138:139] op_sel_hi:[1,0]
	v_pk_mul_f32 v[24:25], v[24:25], v[138:139] op_sel_hi:[1,0]
	v_pk_mul_f32 v[18:19], v[18:19], v[138:139] op_sel_hi:[1,0]
	v_pk_mul_f32 v[20:21], v[20:21], v[138:139] op_sel_hi:[1,0]
	v_pk_mul_f32 v[166:167], v[22:23], v[146:147]
	v_pk_mul_f32 v[168:169], v[24:25], v[146:147]
	v_pk_mul_f32 v[170:171], v[18:19], v[146:147]
	v_pk_mul_f32 v[172:173], v[20:21], v[146:147]
	v_exp_f32_e32 v166, v166
	v_exp_f32_e32 v167, v167
	v_exp_f32_e32 v168, v168
	v_exp_f32_e32 v169, v169
	v_exp_f32_e32 v170, v170
	v_exp_f32_e32 v171, v171
	v_exp_f32_e32 v172, v172
	v_exp_f32_e32 v173, v173
	v_pk_add_f32 v[166:167], v[166:167], 1.0 op_sel_hi:[1,0]
	v_pk_add_f32 v[168:169], v[168:169], 1.0 op_sel_hi:[1,0]
	v_pk_add_f32 v[170:171], v[170:171], 1.0 op_sel_hi:[1,0]
	v_pk_add_f32 v[172:173], v[172:173], 1.0 op_sel_hi:[1,0]
	v_rcp_f32_e32 v166, v166
	v_rcp_f32_e32 v167, v167
	v_rcp_f32_e32 v168, v168
	v_rcp_f32_e32 v169, v169
	v_rcp_f32_e32 v170, v170
	v_rcp_f32_e32 v171, v171
	v_rcp_f32_e32 v172, v172
	v_rcp_f32_e32 v173, v173
	v_cvt_pk_bf16_f32 v22, v166, v167
	v_cvt_pk_bf16_f32 v23, v168, v169
	v_cvt_pk_bf16_f32 v24, v170, v171
	v_cvt_pk_bf16_f32 v25, v172, v173
	global_store_dwordx4 v141, v[22:25], s[56:57] offset:256 sc1
	s_waitcnt lgkmcnt(0)
	v_mov_b32_e32 v138, v231
	v_add_u32_e32 v141, 0x11e000, v140
	v_pk_mul_f32 v[14:15], v[14:15], v[138:139] op_sel_hi:[1,0]
	v_pk_mul_f32 v[16:17], v[16:17], v[138:139] op_sel_hi:[1,0]
	v_pk_mul_f32 v[10:11], v[10:11], v[138:139] op_sel_hi:[1,0]
	v_pk_mul_f32 v[12:13], v[12:13], v[138:139] op_sel_hi:[1,0]
	v_pk_mul_f32 v[166:167], v[14:15], v[146:147]
	v_pk_mul_f32 v[168:169], v[16:17], v[146:147]
	v_pk_mul_f32 v[170:171], v[10:11], v[146:147]
	v_pk_mul_f32 v[172:173], v[12:13], v[146:147]
	v_exp_f32_e32 v166, v166
	v_exp_f32_e32 v167, v167
	v_exp_f32_e32 v168, v168
	v_exp_f32_e32 v169, v169
	v_exp_f32_e32 v170, v170
	v_exp_f32_e32 v171, v171
	v_exp_f32_e32 v172, v172
	v_exp_f32_e32 v173, v173
	v_pk_add_f32 v[166:167], v[166:167], 1.0 op_sel_hi:[1,0]
	v_pk_add_f32 v[168:169], v[168:169], 1.0 op_sel_hi:[1,0]
	v_pk_add_f32 v[170:171], v[170:171], 1.0 op_sel_hi:[1,0]
	v_pk_add_f32 v[172:173], v[172:173], 1.0 op_sel_hi:[1,0]
	v_rcp_f32_e32 v166, v166
	v_rcp_f32_e32 v167, v167
	v_rcp_f32_e32 v168, v168
	v_rcp_f32_e32 v169, v169
	v_rcp_f32_e32 v170, v170
	v_rcp_f32_e32 v171, v171
	v_rcp_f32_e32 v172, v172
	v_rcp_f32_e32 v173, v173
	v_cvt_pk_bf16_f32 v14, v166, v167
	v_cvt_pk_bf16_f32 v15, v168, v169
	v_cvt_pk_bf16_f32 v16, v170, v171
	v_cvt_pk_bf16_f32 v17, v172, v173
	global_store_dwordx4 v141, v[14:17], s[56:57] sc1
	v_pk_mul_f32 v[6:7], v[6:7], v[138:139] op_sel_hi:[1,0]
	v_pk_mul_f32 v[8:9], v[8:9], v[138:139] op_sel_hi:[1,0]
	v_pk_mul_f32 v[2:3], v[2:3], v[138:139] op_sel_hi:[1,0]
	v_pk_mul_f32 v[4:5], v[4:5], v[138:139] op_sel_hi:[1,0]
	v_pk_mul_f32 v[166:167], v[6:7], v[146:147]
	v_pk_mul_f32 v[168:169], v[8:9], v[146:147]
	v_pk_mul_f32 v[170:171], v[2:3], v[146:147]
	v_pk_mul_f32 v[172:173], v[4:5], v[146:147]
	v_exp_f32_e32 v166, v166
	v_exp_f32_e32 v167, v167
	v_exp_f32_e32 v168, v168
	v_exp_f32_e32 v169, v169
	v_exp_f32_e32 v170, v170
	v_exp_f32_e32 v171, v171
	v_exp_f32_e32 v172, v172
	v_exp_f32_e32 v173, v173
	v_pk_add_f32 v[166:167], v[166:167], 1.0 op_sel_hi:[1,0]
	v_pk_add_f32 v[168:169], v[168:169], 1.0 op_sel_hi:[1,0]
	v_pk_add_f32 v[170:171], v[170:171], 1.0 op_sel_hi:[1,0]
	v_pk_add_f32 v[172:173], v[172:173], 1.0 op_sel_hi:[1,0]
	v_rcp_f32_e32 v166, v166
	v_rcp_f32_e32 v167, v167
	v_rcp_f32_e32 v168, v168
	v_rcp_f32_e32 v169, v169
	v_rcp_f32_e32 v170, v170
	v_rcp_f32_e32 v171, v171
	v_rcp_f32_e32 v172, v172
	v_rcp_f32_e32 v173, v173
	v_cvt_pk_bf16_f32 v6, v166, v167
	v_cvt_pk_bf16_f32 v7, v168, v169
	v_cvt_pk_bf16_f32 v8, v170, v171
	v_cvt_pk_bf16_f32 v9, v172, v173
	global_store_dwordx4 v141, v[6:9], s[56:57] offset:256 sc1
	s_branch .Lpj_done
; __device__ __forceinline__ u32x4 pack8(const f32x4 a, const f32x4 b) { u32x4 w; w.x = cvt_pk_bf16(a[0], a[1]); w.y = cvt_pk_bf16(a[2], a[3]); w.z = cvt_pk_bf16(b[0], b[1]); w.w = cvt_pk_bf16(b[2], b[3]); return w; }
;     __device__ __forceinline__ void operator()(const f32x4 (&acc)[2][2][4][2], const Unit& u, int wr, int wc, int fr, int fq) const {
;         const int row0 = u.pm * 256 + wr * 64 + fr; const int kind = u.pn < 7 ? 0 : (u.pn < 12 ? 1 : 2);
;         bf16_t* base = kind == 0 ? P1 : P2; const int ld = kind == 0 ? P1W : P2W; const int col0 = (kind == 0 ? u.pn : u.pn - 7) * 256 + wc * 32 + 8 * fq;
;         const float c3 = kind == 1 ? -LOG2E_ * 1.5957691216f * 0.044715f : 0.f, c1 = kind == 1 ? -LOG2E_ * 1.5957691216f : -LOG2E_;
; #pragma unroll
;         for (int ai = 0; ai < 2; ++ai)
; #pragma unroll
;             for (int m = 0; m < 4; ++m) {
;                 const int row = row0 + ai * 128 + m * 16; const float rs = (u.pm == pm0) ? RS[row & 255] : row_rstd(ss, row);
; #pragma unroll
;                 for (int bj = 0; bj < 2; ++bj) {
;                     f32x4 v[2], e[2];
; #pragma unroll
;                     for (int n = 0; n < 2; ++n) { v[n] = acc[ai][bj][m][n] * rs; e[n] = v[n] * ((v[n] * v[n]) * c3 + c1); }
;                     if (kind != 0) {
; #pragma unroll
;                         for (int n = 0; n < 2; ++n)
; #pragma unroll
;                             for (int j = 0; j < 4; ++j) e[n][j] = __builtin_amdgcn_exp2f(e[n][j]);
; #pragma unroll
;                         for (int n = 0; n < 2; ++n) e[n] = e[n] + 1.0f;
; #pragma unroll
;                         for (int n = 0; n < 2; ++n)
; #pragma unroll
;                             for (int j = 0; j < 4; ++j) e[n][j] = __builtin_amdgcn_rcpf(e[n][j]);
;                         if (kind == 1) { v[0] = v[0] * e[0]; v[1] = v[1] * e[1]; } else { v[0] = e[0]; v[1] = e[1]; }
;                     }
;                     __builtin_nontemporal_store(pack8(v[0], v[1]), (u32x4*)(base + (size_t)row * ld + col0 + bj * 128));
.Lpj_k1:
	s_add_i32 s13, s6, -7
	s_lshl_b32 s13, s13, 8
	v_or_b32_e32 v141, s13, v163
	v_mul_u32_u24_e32 v140, 0x1a00, v140
	v_lshl_add_u32 v140, v141, 1, v140
	v_mov_b32_e32 v144, 0xbdd2d3e7
	v_mov_b32_e32 v145, 0xbdd2d3e7
	v_mov_b32_e32 v146, 0xc0135761
	v_mov_b32_e32 v147, 0xc0135761
	s_waitcnt lgkmcnt(7)
	v_mov_b32_e32 v138, v224
	v_pk_mul_f32 v[126:127], v[126:127], v[138:139] op_sel_hi:[1,0]
	v_pk_mul_f32 v[128:129], v[128:129], v[138:139] op_sel_hi:[1,0]
	v_pk_mul_f32 v[122:123], v[122:123], v[138:139] op_sel_hi:[1,0]
	v_pk_mul_f32 v[124:125], v[124:125], v[138:139] op_sel_hi:[1,0]
	v_pk_mul_f32 v[166:167], v[126:127], v[126:127]
	v_pk_mul_f32 v[168:169], v[128:129], v[128:129]
	v_pk_mul_f32 v[170:171], v[122:123], v[122:123]
	v_pk_mul_f32 v[172:173], v[124:125], v[124:125]
	v_pk_fma_f32 v[166:167], v[144:145], v[166:167], v[146:147]
	v_pk_fma_f32 v[168:169], v[144:145], v[168:169], v[146:147]
	v_pk_fma_f32 v[170:171], v[144:145], v[170:171], v[146:147]
	v_pk_fma_f32 v[172:173], v[144:145], v[172:173], v[146:147]
	v_pk_mul_f32 v[166:167], v[126:127], v[166:167]
	v_pk_mul_f32 v[168:169], v[128:129], v[168:169]
	v_pk_mul_f32 v[170:171], v[122:123], v[170:171]
	v_pk_mul_f32 v[172:173], v[124:125], v[172:173]
	v_exp_f32_e32 v166, v166
	v_exp_f32_e32 v167, v167
	v_exp_f32_e32 v168, v168
	v_exp_f32_e32 v169, v169
	v_exp_f32_e32 v170, v170
	v_exp_f32_e32 v171, v171
	v_exp_f32_e32 v172, v172
	v_exp_f32_e32 v173, v173
	v_pk_add_f32 v[166:167], v[166:167], 1.0 op_sel_hi:[1,0]
	v_pk_add_f32 v[168:169], v[168:169], 1.0 op_sel_hi:[1,0]
	v_pk_add_f32 v[170:171], v[170:171], 1.0 op_sel_hi:[1,0]
	v_pk_add_f32 v[172:173], v[172:173], 1.0 op_sel_hi:[1,0]
	v_rcp_f32_e32 v166, v166
	v_rcp_f32_e32 v167, v167
	v_rcp_f32_e32 v168, v168
	v_rcp_f32_e32 v169, v169
	v_rcp_f32_e32 v170, v170
	v_rcp_f32_e32 v171, v171
	v_rcp_f32_e32 v172, v172
	v_rcp_f32_e32 v173, v173
	v_pk_mul_f32 v[126:127], v[126:127], v[166:167]
	v_pk_mul_f32 v[128:129], v[128:129], v[168:169]
	v_pk_mul_f32 v[122:123], v[122:123], v[170:171]
	v_pk_mul_f32 v[124:125], v[124:125], v[172:173]
	v_cvt_pk_bf16_f32 v126, v126, v127
	v_cvt_pk_bf16_f32 v127, v128, v129
	v_cvt_pk_bf16_f32 v128, v122, v123
	v_cvt_pk_bf16_f32 v129, v124, v125
	global_store_dwordx4 v140, v[126:129], s[56:57] sc1
	v_pk_mul_f32 v[118:119], v[118:119], v[138:139] op_sel_hi:[1,0]
	v_pk_mul_f32 v[120:121], v[120:121], v[138:139] op_sel_hi:[1,0]
	v_pk_mul_f32 v[114:115], v[114:115], v[138:139] op_sel_hi:[1,0]
	v_pk_mul_f32 v[116:117], v[116:117], v[138:139] op_sel_hi:[1,0]
	v_pk_mul_f32 v[166:167], v[118:119], v[118:119]
	v_pk_mul_f32 v[168:169], v[120:121], v[120:121]
	v_pk_mul_f32 v[170:171], v[114:115], v[114:115]
	v_pk_mul_f32 v[172:173], v[116:117], v[116:117]
	v_pk_fma_f32 v[166:167], v[144:145], v[166:167], v[146:147]
	v_pk_fma_f32 v[168:169], v[144:145], v[168:169], v[146:147]
	v_pk_fma_f32 v[170:171], v[144:145], v[170:171], v[146:147]
	v_pk_fma_f32 v[172:173], v[144:145], v[172:173], v[146:147]
	v_pk_mul_f32 v[166:167], v[118:119], v[166:167]
	v_pk_mul_f32 v[168:169], v[120:121], v[168:169]
	v_pk_mul_f32 v[170:171], v[114:115], v[170:171]
	v_pk_mul_f32 v[172:173], v[116:117], v[172:173]
	v_exp_f32_e32 v166, v166
	v_exp_f32_e32 v167, v167
	v_exp_f32_e32 v168, v168
	v_exp_f32_e32 v169, v169
	v_exp_f32_e32 v170, v170
	v_exp_f32_e32 v171, v171
	v_exp_f32_e32 v172, v172
	v_exp_f32_e32 v173, v173
	v_pk_add_f32 v[166:167], v[166:167], 1.0 op_sel_hi:[1,0]
	v_pk_add_f32 v[168:169], v[168:169], 1.0 op_sel_hi:[1,0]
	v_pk_add_f32 v[170:171], v[170:171], 1.0 op_sel_hi:[1,0]
	v_pk_add_f32 v[172:173], v[172:173], 1.0 op_sel_hi:[1,0]
	v_rcp_f32_e32 v166, v166
	v_rcp_f32_e32 v167, v167
	v_rcp_f32_e32 v168, v168
	v_rcp_f32_e32 v169, v169
	v_rcp_f32_e32 v170, v170
	v_rcp_f32_e32 v171, v171
	v_rcp_f32_e32 v172, v172
	v_rcp_f32_e32 v173, v173
	v_pk_mul_f32 v[118:119], v[118:119], v[166:167]
	v_pk_mul_f32 v[120:121], v[120:121], v[168:169]
	v_pk_mul_f32 v[114:115], v[114:115], v[170:171]
	v_pk_mul_f32 v[116:117], v[116:117], v[172:173]
	v_cvt_pk_bf16_f32 v118, v118, v119
	v_cvt_pk_bf16_f32 v119, v120, v121
	v_cvt_pk_bf16_f32 v120, v114, v115
	v_cvt_pk_bf16_f32 v121, v116, v117
	global_store_dwordx4 v140, v[118:121], s[56:57] offset:256 sc1
	s_waitcnt lgkmcnt(6)
; __device__ __forceinline__ u32x4 pack8(const f32x4 a, const f32x4 b) { u32x4 w; w.x = cvt_pk_bf16(a[0], a[1]); w.y = cvt_pk_bf16(a[2], a[3]); w.z = cvt_pk_bf16(b[0], b[1]); w.w = cvt_pk_bf16(b[2], b[3]); return w; }
;     __device__ __forceinline__ void operator()(const f32x4 (&acc)[2][2][4][2], const Unit& u, int wr, int wc, int fr, int fq) const {
;     ...
;                 const int row = row0 + ai * 128 + m * 16; const float rs = (u.pm == pm0) ? RS[row & 255] : row_rstd(ss, row);
; #pragma unroll
;                 for (int bj = 0; bj < 2; ++bj) {
;                     f32x4 v[2], e[2];
; #pragma unroll
;                     for (int n = 0; n < 2; ++n) { v[n] = acc[ai][bj][m][n] * rs; e[n] = v[n] * ((v[n] * v[n]) * c3 + c1); }
;                     if (kind != 0) {
; #pragma unroll
;                         for (int n = 0; n < 2; ++n)
; #pragma unroll
;                             for (int j = 0; j < 4; ++j) e[n][j] = __builtin_amdgcn_exp2f(e[n][j]);
; #pragma unroll
;                         for (int n = 0; n < 2; ++n) e[n] = e[n] + 1.0f;
; #pragma unroll
;                         for (int n = 0; n < 2; ++n)
; #pragma unroll
;                             for (int j = 0; j < 4; ++j) e[n][j] = __builtin_amdgcn_rcpf(e[n][j]);
;                         if (kind == 1) { v[0] = v[0] * e[0]; v[1] = v[1] * e[1]; } else { v[0] = e[0]; v[1] = e[1]; }
;                     }
;                     __builtin_nontemporal_store(pack8(v[0], v[1]), (u32x4*)(base + (size_t)row * ld + col0 + bj * 128));
	v_mov_b32_e32 v138, v225
	v_add_u32_e32 v141, 0x1a000, v140
	v_pk_mul_f32 v[110:111], v[110:111], v[138:139] op_sel_hi:[1,0]
	v_pk_mul_f32 v[112:113], v[112:113], v[138:139] op_sel_hi:[1,0]
	v_pk_mul_f32 v[106:107], v[106:107], v[138:139] op_sel_hi:[1,0]
	v_pk_mul_f32 v[108:109], v[108:109], v[138:139] op_sel_hi:[1,0]
	v_pk_mul_f32 v[166:167], v[110:111], v[110:111]
	v_pk_mul_f32 v[168:169], v[112:113], v[112:113]
	v_pk_mul_f32 v[170:171], v[106:107], v[106:107]
	v_pk_mul_f32 v[172:173], v[108:109], v[108:109]
	v_pk_fma_f32 v[166:167], v[144:145], v[166:167], v[146:147]
	v_pk_fma_f32 v[168:169], v[144:145], v[168:169], v[146:147]
	v_pk_fma_f32 v[170:171], v[144:145], v[170:171], v[146:147]
	v_pk_fma_f32 v[172:173], v[144:145], v[172:173], v[146:147]
	v_pk_mul_f32 v[166:167], v[110:111], v[166:167]
	v_pk_mul_f32 v[168:169], v[112:113], v[168:169]
	v_pk_mul_f32 v[170:171], v[106:107], v[170:171]
	v_pk_mul_f32 v[172:173], v[108:109], v[172:173]
	v_exp_f32_e32 v166, v166
	v_exp_f32_e32 v167, v167
	v_exp_f32_e32 v168, v168
	v_exp_f32_e32 v169, v169
	v_exp_f32_e32 v170, v170
	v_exp_f32_e32 v171, v171
	v_exp_f32_e32 v172, v172
	v_exp_f32_e32 v173, v173
	v_pk_add_f32 v[166:167], v[166:167], 1.0 op_sel_hi:[1,0]
	v_pk_add_f32 v[168:169], v[168:169], 1.0 op_sel_hi:[1,0]
	v_pk_add_f32 v[170:171], v[170:171], 1.0 op_sel_hi:[1,0]
	v_pk_add_f32 v[172:173], v[172:173], 1.0 op_sel_hi:[1,0]
	v_rcp_f32_e32 v166, v166
	v_rcp_f32_e32 v167, v167
	v_rcp_f32_e32 v168, v168
	v_rcp_f32_e32 v169, v169
	v_rcp_f32_e32 v170, v170
	v_rcp_f32_e32 v171, v171
	v_rcp_f32_e32 v172, v172
	v_rcp_f32_e32 v173, v173
	v_pk_mul_f32 v[110:111], v[110:111], v[166:167]
	v_pk_mul_f32 v[112:113], v[112:113], v[168:169]
	v_pk_mul_f32 v[106:107], v[106:107], v[170:171]
	v_pk_mul_f32 v[108:109], v[108:109], v[172:173]
	v_cvt_pk_bf16_f32 v110, v110, v111
	v_cvt_pk_bf16_f32 v111, v112, v113
	v_cvt_pk_bf16_f32 v112, v106, v107
	v_cvt_pk_bf16_f32 v113, v108, v109
	global_store_dwordx4 v141, v[110:113], s[56:57] sc1
	v_pk_mul_f32 v[102:103], v[102:103], v[138:139] op_sel_hi:[1,0]
	v_pk_mul_f32 v[104:105], v[104:105], v[138:139] op_sel_hi:[1,0]
	v_pk_mul_f32 v[98:99], v[98:99], v[138:139] op_sel_hi:[1,0]
	v_pk_mul_f32 v[100:101], v[100:101], v[138:139] op_sel_hi:[1,0]
	v_pk_mul_f32 v[166:167], v[102:103], v[102:103]
	v_pk_mul_f32 v[168:169], v[104:105], v[104:105]
	v_pk_mul_f32 v[170:171], v[98:99], v[98:99]
	v_pk_mul_f32 v[172:173], v[100:101], v[100:101]
	v_pk_fma_f32 v[166:167], v[144:145], v[166:167], v[146:147]
	v_pk_fma_f32 v[168:169], v[144:145], v[168:169], v[146:147]
	v_pk_fma_f32 v[170:171], v[144:145], v[170:171], v[146:147]
	v_pk_fma_f32 v[172:173], v[144:145], v[172:173], v[146:147]
	v_pk_mul_f32 v[166:167], v[102:103], v[166:167]
	v_pk_mul_f32 v[168:169], v[104:105], v[168:169]
	v_pk_mul_f32 v[170:171], v[98:99], v[170:171]
	v_pk_mul_f32 v[172:173], v[100:101], v[172:173]
	v_exp_f32_e32 v166, v166
	v_exp_f32_e32 v167, v167
	v_exp_f32_e32 v168, v168
	v_exp_f32_e32 v169, v169
	v_exp_f32_e32 v170, v170
	v_exp_f32_e32 v171, v171
	v_exp_f32_e32 v172, v172
	v_exp_f32_e32 v173, v173
	v_pk_add_f32 v[166:167], v[166:167], 1.0 op_sel_hi:[1,0]
	v_pk_add_f32 v[168:169], v[168:169], 1.0 op_sel_hi:[1,0]
	v_pk_add_f32 v[170:171], v[170:171], 1.0 op_sel_hi:[1,0]
	v_pk_add_f32 v[172:173], v[172:173], 1.0 op_sel_hi:[1,0]
	v_rcp_f32_e32 v166, v166
	v_rcp_f32_e32 v167, v167
	v_rcp_f32_e32 v168, v168
	v_rcp_f32_e32 v169, v169
	v_rcp_f32_e32 v170, v170
	v_rcp_f32_e32 v171, v171
	v_rcp_f32_e32 v172, v172
	v_rcp_f32_e32 v173, v173
	v_pk_mul_f32 v[102:103], v[102:103], v[166:167]
	v_pk_mul_f32 v[104:105], v[104:105], v[168:169]
	v_pk_mul_f32 v[98:99], v[98:99], v[170:171]
	v_pk_mul_f32 v[100:101], v[100:101], v[172:173]
	v_cvt_pk_bf16_f32 v102, v102, v103
	v_cvt_pk_bf16_f32 v103, v104, v105
	v_cvt_pk_bf16_f32 v104, v98, v99
	v_cvt_pk_bf16_f32 v105, v100, v101
	global_store_dwordx4 v141, v[102:105], s[56:57] offset:256 sc1
	s_waitcnt lgkmcnt(5)
	v_mov_b32_e32 v138, v226
	v_add_u32_e32 v141, 0x34000, v140
	v_pk_mul_f32 v[94:95], v[94:95], v[138:139] op_sel_hi:[1,0]
	v_pk_mul_f32 v[96:97], v[96:97], v[138:139] op_sel_hi:[1,0]
	v_pk_mul_f32 v[90:91], v[90:91], v[138:139] op_sel_hi:[1,0]
	v_pk_mul_f32 v[92:93], v[92:93], v[138:139] op_sel_hi:[1,0]
	v_pk_mul_f32 v[166:167], v[94:95], v[94:95]
	v_pk_mul_f32 v[168:169], v[96:97], v[96:97]
	v_pk_mul_f32 v[170:171], v[90:91], v[90:91]
	v_pk_mul_f32 v[172:173], v[92:93], v[92:93]
	v_pk_fma_f32 v[166:167], v[144:145], v[166:167], v[146:147]
	v_pk_fma_f32 v[168:169], v[144:145], v[168:169], v[146:147]
	v_pk_fma_f32 v[170:171], v[144:145], v[170:171], v[146:147]
	v_pk_fma_f32 v[172:173], v[144:145], v[172:173], v[146:147]
	v_pk_mul_f32 v[166:167], v[94:95], v[166:167]
	v_pk_mul_f32 v[168:169], v[96:97], v[168:169]
	v_pk_mul_f32 v[170:171], v[90:91], v[170:171]
	v_pk_mul_f32 v[172:173], v[92:93], v[172:173]
	v_exp_f32_e32 v166, v166
	v_exp_f32_e32 v167, v167
	v_exp_f32_e32 v168, v168
	v_exp_f32_e32 v169, v169
	v_exp_f32_e32 v170, v170
	v_exp_f32_e32 v171, v171
	v_exp_f32_e32 v172, v172
	v_exp_f32_e32 v173, v173
	v_pk_add_f32 v[166:167], v[166:167], 1.0 op_sel_hi:[1,0]
	v_pk_add_f32 v[168:169], v[168:169], 1.0 op_sel_hi:[1,0]
	v_pk_add_f32 v[170:171], v[170:171], 1.0 op_sel_hi:[1,0]
	v_pk_add_f32 v[172:173], v[172:173], 1.0 op_sel_hi:[1,0]
	v_rcp_f32_e32 v166, v166
	v_rcp_f32_e32 v167, v167
	v_rcp_f32_e32 v168, v168
	v_rcp_f32_e32 v169, v169
	v_rcp_f32_e32 v170, v170
	v_rcp_f32_e32 v171, v171
	v_rcp_f32_e32 v172, v172
	v_rcp_f32_e32 v173, v173
	v_pk_mul_f32 v[94:95], v[94:95], v[166:167]
	v_pk_mul_f32 v[96:97], v[96:97], v[168:169]
	v_pk_mul_f32 v[90:91], v[90:91], v[170:171]
; __device__ __forceinline__ u32x4 pack8(const f32x4 a, const f32x4 b) { u32x4 w; w.x = cvt_pk_bf16(a[0], a[1]); w.y = cvt_pk_bf16(a[2], a[3]); w.z = cvt_pk_bf16(b[0], b[1]); w.w = cvt_pk_bf16(b[2], b[3]); return w; }
;     __device__ __forceinline__ void operator()(const f32x4 (&acc)[2][2][4][2], const Unit& u, int wr, int wc, int fr, int fq) const {
;     ...
;                 const int row = row0 + ai * 128 + m * 16; const float rs = (u.pm == pm0) ? RS[row & 255] : row_rstd(ss, row);
; #pragma unroll
;                 for (int bj = 0; bj < 2; ++bj) {
;                     f32x4 v[2], e[2];
; #pragma unroll
;                     for (int n = 0; n < 2; ++n) { v[n] = acc[ai][bj][m][n] * rs; e[n] = v[n] * ((v[n] * v[n]) * c3 + c1); }
;                     if (kind != 0) {
; #pragma unroll
;                         for (int n = 0; n < 2; ++n)
; #pragma unroll
;                             for (int j = 0; j < 4; ++j) e[n][j] = __builtin_amdgcn_exp2f(e[n][j]);
; #pragma unroll
;                         for (int n = 0; n < 2; ++n) e[n] = e[n] + 1.0f;
; #pragma unroll
;                         for (int n = 0; n < 2; ++n)
; #pragma unroll
;                             for (int j = 0; j < 4; ++j) e[n][j] = __builtin_amdgcn_rcpf(e[n][j]);
;                         if (kind == 1) { v[0] = v[0] * e[0]; v[1] = v[1] * e[1]; } else { v[0] = e[0]; v[1] = e[1]; }
;                     }
;                     __builtin_nontemporal_store(pack8(v[0], v[1]), (u32x4*)(base + (size_t)row * ld + col0 + bj * 128));
	v_pk_mul_f32 v[92:93], v[92:93], v[172:173]
	v_cvt_pk_bf16_f32 v94, v94, v95
	v_cvt_pk_bf16_f32 v95, v96, v97
	v_cvt_pk_bf16_f32 v96, v90, v91
	v_cvt_pk_bf16_f32 v97, v92, v93
	global_store_dwordx4 v141, v[94:97], s[56:57] sc1
	v_pk_mul_f32 v[86:87], v[86:87], v[138:139] op_sel_hi:[1,0]
	v_pk_mul_f32 v[88:89], v[88:89], v[138:139] op_sel_hi:[1,0]
	v_pk_mul_f32 v[82:83], v[82:83], v[138:139] op_sel_hi:[1,0]
	v_pk_mul_f32 v[84:85], v[84:85], v[138:139] op_sel_hi:[1,0]
	v_pk_mul_f32 v[166:167], v[86:87], v[86:87]
	v_pk_mul_f32 v[168:169], v[88:89], v[88:89]
	v_pk_mul_f32 v[170:171], v[82:83], v[82:83]
	v_pk_mul_f32 v[172:173], v[84:85], v[84:85]
	v_pk_fma_f32 v[166:167], v[144:145], v[166:167], v[146:147]
	v_pk_fma_f32 v[168:169], v[144:145], v[168:169], v[146:147]
	v_pk_fma_f32 v[170:171], v[144:145], v[170:171], v[146:147]
	v_pk_fma_f32 v[172:173], v[144:145], v[172:173], v[146:147]
	v_pk_mul_f32 v[166:167], v[86:87], v[166:167]
	v_pk_mul_f32 v[168:169], v[88:89], v[168:169]
	v_pk_mul_f32 v[170:171], v[82:83], v[170:171]
	v_pk_mul_f32 v[172:173], v[84:85], v[172:173]
	v_exp_f32_e32 v166, v166
	v_exp_f32_e32 v167, v167
	v_exp_f32_e32 v168, v168
	v_exp_f32_e32 v169, v169
	v_exp_f32_e32 v170, v170
	v_exp_f32_e32 v171, v171
	v_exp_f32_e32 v172, v172
	v_exp_f32_e32 v173, v173
	v_pk_add_f32 v[166:167], v[166:167], 1.0 op_sel_hi:[1,0]
	v_pk_add_f32 v[168:169], v[168:169], 1.0 op_sel_hi:[1,0]
	v_pk_add_f32 v[170:171], v[170:171], 1.0 op_sel_hi:[1,0]
	v_pk_add_f32 v[172:173], v[172:173], 1.0 op_sel_hi:[1,0]
	v_rcp_f32_e32 v166, v166
	v_rcp_f32_e32 v167, v167
	v_rcp_f32_e32 v168, v168
	v_rcp_f32_e32 v169, v169
	v_rcp_f32_e32 v170, v170
	v_rcp_f32_e32 v171, v171
	v_rcp_f32_e32 v172, v172
	v_rcp_f32_e32 v173, v173
	v_pk_mul_f32 v[86:87], v[86:87], v[166:167]
	v_pk_mul_f32 v[88:89], v[88:89], v[168:169]
	v_pk_mul_f32 v[82:83], v[82:83], v[170:171]
	v_pk_mul_f32 v[84:85], v[84:85], v[172:173]
	v_cvt_pk_bf16_f32 v86, v86, v87
	v_cvt_pk_bf16_f32 v87, v88, v89
	v_cvt_pk_bf16_f32 v88, v82, v83
	v_cvt_pk_bf16_f32 v89, v84, v85
	global_store_dwordx4 v141, v[86:89], s[56:57] offset:256 sc1
	s_waitcnt lgkmcnt(4)
	v_mov_b32_e32 v138, v227
	v_add_u32_e32 v141, 0x4e000, v140
	v_pk_mul_f32 v[78:79], v[78:79], v[138:139] op_sel_hi:[1,0]
	v_pk_mul_f32 v[80:81], v[80:81], v[138:139] op_sel_hi:[1,0]
	v_pk_mul_f32 v[74:75], v[74:75], v[138:139] op_sel_hi:[1,0]
	v_pk_mul_f32 v[76:77], v[76:77], v[138:139] op_sel_hi:[1,0]
	v_pk_mul_f32 v[166:167], v[78:79], v[78:79]
	v_pk_mul_f32 v[168:169], v[80:81], v[80:81]
	v_pk_mul_f32 v[170:171], v[74:75], v[74:75]
	v_pk_mul_f32 v[172:173], v[76:77], v[76:77]
	v_pk_fma_f32 v[166:167], v[144:145], v[166:167], v[146:147]
	v_pk_fma_f32 v[168:169], v[144:145], v[168:169], v[146:147]
	v_pk_fma_f32 v[170:171], v[144:145], v[170:171], v[146:147]
	v_pk_fma_f32 v[172:173], v[144:145], v[172:173], v[146:147]
	v_pk_mul_f32 v[166:167], v[78:79], v[166:167]
	v_pk_mul_f32 v[168:169], v[80:81], v[168:169]
	v_pk_mul_f32 v[170:171], v[74:75], v[170:171]
	v_pk_mul_f32 v[172:173], v[76:77], v[172:173]
	v_exp_f32_e32 v166, v166
	v_exp_f32_e32 v167, v167
	v_exp_f32_e32 v168, v168
	v_exp_f32_e32 v169, v169
	v_exp_f32_e32 v170, v170
	v_exp_f32_e32 v171, v171
	v_exp_f32_e32 v172, v172
	v_exp_f32_e32 v173, v173
	v_pk_add_f32 v[166:167], v[166:167], 1.0 op_sel_hi:[1,0]
	v_pk_add_f32 v[168:169], v[168:169], 1.0 op_sel_hi:[1,0]
	v_pk_add_f32 v[170:171], v[170:171], 1.0 op_sel_hi:[1,0]
	v_pk_add_f32 v[172:173], v[172:173], 1.0 op_sel_hi:[1,0]
	v_rcp_f32_e32 v166, v166
	v_rcp_f32_e32 v167, v167
	v_rcp_f32_e32 v168, v168
	v_rcp_f32_e32 v169, v169
	v_rcp_f32_e32 v170, v170
	v_rcp_f32_e32 v171, v171
	v_rcp_f32_e32 v172, v172
	v_rcp_f32_e32 v173, v173
	v_pk_mul_f32 v[78:79], v[78:79], v[166:167]
	v_pk_mul_f32 v[80:81], v[80:81], v[168:169]
	v_pk_mul_f32 v[74:75], v[74:75], v[170:171]
	v_pk_mul_f32 v[76:77], v[76:77], v[172:173]
	v_cvt_pk_bf16_f32 v78, v78, v79
	v_cvt_pk_bf16_f32 v79, v80, v81
	v_cvt_pk_bf16_f32 v80, v74, v75
	v_cvt_pk_bf16_f32 v81, v76, v77
	global_store_dwordx4 v141, v[78:81], s[56:57] sc1
	v_pk_mul_f32 v[70:71], v[70:71], v[138:139] op_sel_hi:[1,0]
	v_pk_mul_f32 v[72:73], v[72:73], v[138:139] op_sel_hi:[1,0]
	v_pk_mul_f32 v[66:67], v[66:67], v[138:139] op_sel_hi:[1,0]
	v_pk_mul_f32 v[68:69], v[68:69], v[138:139] op_sel_hi:[1,0]
	v_pk_mul_f32 v[166:167], v[70:71], v[70:71]
	v_pk_mul_f32 v[168:169], v[72:73], v[72:73]
	v_pk_mul_f32 v[170:171], v[66:67], v[66:67]
	v_pk_mul_f32 v[172:173], v[68:69], v[68:69]
	v_pk_fma_f32 v[166:167], v[144:145], v[166:167], v[146:147]
	v_pk_fma_f32 v[168:169], v[144:145], v[168:169], v[146:147]
	v_pk_fma_f32 v[170:171], v[144:145], v[170:171], v[146:147]
	v_pk_fma_f32 v[172:173], v[144:145], v[172:173], v[146:147]
	v_pk_mul_f32 v[166:167], v[70:71], v[166:167]
	v_pk_mul_f32 v[168:169], v[72:73], v[168:169]
	v_pk_mul_f32 v[170:171], v[66:67], v[170:171]
	v_pk_mul_f32 v[172:173], v[68:69], v[172:173]
	v_exp_f32_e32 v166, v166
	v_exp_f32_e32 v167, v167
	v_exp_f32_e32 v168, v168
	v_exp_f32_e32 v169, v169
	v_exp_f32_e32 v170, v170
	v_exp_f32_e32 v171, v171
	v_exp_f32_e32 v172, v172
	v_exp_f32_e32 v173, v173
	v_pk_add_f32 v[166:167], v[166:167], 1.0 op_sel_hi:[1,0]
	v_pk_add_f32 v[168:169], v[168:169], 1.0 op_sel_hi:[1,0]
	v_pk_add_f32 v[170:171], v[170:171], 1.0 op_sel_hi:[1,0]
	v_pk_add_f32 v[172:173], v[172:173], 1.0 op_sel_hi:[1,0]
	v_rcp_f32_e32 v166, v166
	v_rcp_f32_e32 v167, v167
	v_rcp_f32_e32 v168, v168
	v_rcp_f32_e32 v169, v169
	v_rcp_f32_e32 v170, v170
	v_rcp_f32_e32 v171, v171
	v_rcp_f32_e32 v172, v172
	v_rcp_f32_e32 v173, v173
	v_pk_mul_f32 v[70:71], v[70:71], v[166:167]
	v_pk_mul_f32 v[72:73], v[72:73], v[168:169]
	v_pk_mul_f32 v[66:67], v[66:67], v[170:171]
	v_pk_mul_f32 v[68:69], v[68:69], v[172:173]
	v_cvt_pk_bf16_f32 v70, v70, v71
	v_cvt_pk_bf16_f32 v71, v72, v73
	v_cvt_pk_bf16_f32 v72, v66, v67
	v_cvt_pk_bf16_f32 v73, v68, v69
	global_store_dwordx4 v141, v[70:73], s[56:57] offset:256 sc1
	s_waitcnt lgkmcnt(3)
; __device__ __forceinline__ u32x4 pack8(const f32x4 a, const f32x4 b) { u32x4 w; w.x = cvt_pk_bf16(a[0], a[1]); w.y = cvt_pk_bf16(a[2], a[3]); w.z = cvt_pk_bf16(b[0], b[1]); w.w = cvt_pk_bf16(b[2], b[3]); return w; }
;     __device__ __forceinline__ void operator()(const f32x4 (&acc)[2][2][4][2], const Unit& u, int wr, int wc, int fr, int fq) const {
;     ...
;                 const int row = row0 + ai * 128 + m * 16; const float rs = (u.pm == pm0) ? RS[row & 255] : row_rstd(ss, row);
; #pragma unroll
;                 for (int bj = 0; bj < 2; ++bj) {
;                     f32x4 v[2], e[2];
; #pragma unroll
;                     for (int n = 0; n < 2; ++n) { v[n] = acc[ai][bj][m][n] * rs; e[n] = v[n] * ((v[n] * v[n]) * c3 + c1); }
;                     if (kind != 0) {
; #pragma unroll
;                         for (int n = 0; n < 2; ++n)
; #pragma unroll
;                             for (int j = 0; j < 4; ++j) e[n][j] = __builtin_amdgcn_exp2f(e[n][j]);
; #pragma unroll
;                         for (int n = 0; n < 2; ++n) e[n] = e[n] + 1.0f;
; #pragma unroll
;                         for (int n = 0; n < 2; ++n)
; #pragma unroll
;                             for (int j = 0; j < 4; ++j) e[n][j] = __builtin_amdgcn_rcpf(e[n][j]);
;                         if (kind == 1) { v[0] = v[0] * e[0]; v[1] = v[1] * e[1]; } else { v[0] = e[0]; v[1] = e[1]; }
;                     }
;                     __builtin_nontemporal_store(pack8(v[0], v[1]), (u32x4*)(base + (size_t)row * ld + col0 + bj * 128));
	v_mov_b32_e32 v138, v228
	v_add_u32_e32 v141, 0xd0000, v140
	v_pk_mul_f32 v[62:63], v[62:63], v[138:139] op_sel_hi:[1,0]
	v_pk_mul_f32 v[64:65], v[64:65], v[138:139] op_sel_hi:[1,0]
	v_pk_mul_f32 v[58:59], v[58:59], v[138:139] op_sel_hi:[1,0]
	v_pk_mul_f32 v[60:61], v[60:61], v[138:139] op_sel_hi:[1,0]
	v_pk_mul_f32 v[166:167], v[62:63], v[62:63]
	v_pk_mul_f32 v[168:169], v[64:65], v[64:65]
	v_pk_mul_f32 v[170:171], v[58:59], v[58:59]
	v_pk_mul_f32 v[172:173], v[60:61], v[60:61]
	v_pk_fma_f32 v[166:167], v[144:145], v[166:167], v[146:147]
	v_pk_fma_f32 v[168:169], v[144:145], v[168:169], v[146:147]
	v_pk_fma_f32 v[170:171], v[144:145], v[170:171], v[146:147]
	v_pk_fma_f32 v[172:173], v[144:145], v[172:173], v[146:147]
	v_pk_mul_f32 v[166:167], v[62:63], v[166:167]
	v_pk_mul_f32 v[168:169], v[64:65], v[168:169]
	v_pk_mul_f32 v[170:171], v[58:59], v[170:171]
	v_pk_mul_f32 v[172:173], v[60:61], v[172:173]
	v_exp_f32_e32 v166, v166
	v_exp_f32_e32 v167, v167
	v_exp_f32_e32 v168, v168
	v_exp_f32_e32 v169, v169
	v_exp_f32_e32 v170, v170
	v_exp_f32_e32 v171, v171
	v_exp_f32_e32 v172, v172
	v_exp_f32_e32 v173, v173
	v_pk_add_f32 v[166:167], v[166:167], 1.0 op_sel_hi:[1,0]
	v_pk_add_f32 v[168:169], v[168:169], 1.0 op_sel_hi:[1,0]
	v_pk_add_f32 v[170:171], v[170:171], 1.0 op_sel_hi:[1,0]
	v_pk_add_f32 v[172:173], v[172:173], 1.0 op_sel_hi:[1,0]
	v_rcp_f32_e32 v166, v166
	v_rcp_f32_e32 v167, v167
	v_rcp_f32_e32 v168, v168
	v_rcp_f32_e32 v169, v169
	v_rcp_f32_e32 v170, v170
	v_rcp_f32_e32 v171, v171
	v_rcp_f32_e32 v172, v172
	v_rcp_f32_e32 v173, v173
	v_pk_mul_f32 v[62:63], v[62:63], v[166:167]
	v_pk_mul_f32 v[64:65], v[64:65], v[168:169]
	v_pk_mul_f32 v[58:59], v[58:59], v[170:171]
	v_pk_mul_f32 v[60:61], v[60:61], v[172:173]
	v_cvt_pk_bf16_f32 v62, v62, v63
	v_cvt_pk_bf16_f32 v63, v64, v65
	v_cvt_pk_bf16_f32 v64, v58, v59
	v_cvt_pk_bf16_f32 v65, v60, v61
	global_store_dwordx4 v141, v[62:65], s[56:57] sc1
	v_pk_mul_f32 v[54:55], v[54:55], v[138:139] op_sel_hi:[1,0]
	v_pk_mul_f32 v[56:57], v[56:57], v[138:139] op_sel_hi:[1,0]
	v_pk_mul_f32 v[50:51], v[50:51], v[138:139] op_sel_hi:[1,0]
	v_pk_mul_f32 v[52:53], v[52:53], v[138:139] op_sel_hi:[1,0]
	v_pk_mul_f32 v[166:167], v[54:55], v[54:55]
	v_pk_mul_f32 v[168:169], v[56:57], v[56:57]
	v_pk_mul_f32 v[170:171], v[50:51], v[50:51]
	v_pk_mul_f32 v[172:173], v[52:53], v[52:53]
	v_pk_fma_f32 v[166:167], v[144:145], v[166:167], v[146:147]
	v_pk_fma_f32 v[168:169], v[144:145], v[168:169], v[146:147]
	v_pk_fma_f32 v[170:171], v[144:145], v[170:171], v[146:147]
	v_pk_fma_f32 v[172:173], v[144:145], v[172:173], v[146:147]
	v_pk_mul_f32 v[166:167], v[54:55], v[166:167]
	v_pk_mul_f32 v[168:169], v[56:57], v[168:169]
	v_pk_mul_f32 v[170:171], v[50:51], v[170:171]
	v_pk_mul_f32 v[172:173], v[52:53], v[172:173]
	v_exp_f32_e32 v166, v166
	v_exp_f32_e32 v167, v167
	v_exp_f32_e32 v168, v168
	v_exp_f32_e32 v169, v169
	v_exp_f32_e32 v170, v170
	v_exp_f32_e32 v171, v171
	v_exp_f32_e32 v172, v172
	v_exp_f32_e32 v173, v173
	v_pk_add_f32 v[166:167], v[166:167], 1.0 op_sel_hi:[1,0]
	v_pk_add_f32 v[168:169], v[168:169], 1.0 op_sel_hi:[1,0]
	v_pk_add_f32 v[170:171], v[170:171], 1.0 op_sel_hi:[1,0]
	v_pk_add_f32 v[172:173], v[172:173], 1.0 op_sel_hi:[1,0]
	v_rcp_f32_e32 v166, v166
	v_rcp_f32_e32 v167, v167
	v_rcp_f32_e32 v168, v168
	v_rcp_f32_e32 v169, v169
	v_rcp_f32_e32 v170, v170
	v_rcp_f32_e32 v171, v171
	v_rcp_f32_e32 v172, v172
	v_rcp_f32_e32 v173, v173
	v_pk_mul_f32 v[54:55], v[54:55], v[166:167]
	v_pk_mul_f32 v[56:57], v[56:57], v[168:169]
	v_pk_mul_f32 v[50:51], v[50:51], v[170:171]
	v_pk_mul_f32 v[52:53], v[52:53], v[172:173]
	v_cvt_pk_bf16_f32 v54, v54, v55
	v_cvt_pk_bf16_f32 v55, v56, v57
	v_cvt_pk_bf16_f32 v56, v50, v51
	v_cvt_pk_bf16_f32 v57, v52, v53
	global_store_dwordx4 v141, v[54:57], s[56:57] offset:256 sc1
	s_waitcnt lgkmcnt(2)
	v_mov_b32_e32 v138, v229
	v_add_u32_e32 v141, 0xea000, v140
	v_pk_mul_f32 v[46:47], v[46:47], v[138:139] op_sel_hi:[1,0]
	v_pk_mul_f32 v[48:49], v[48:49], v[138:139] op_sel_hi:[1,0]
	v_pk_mul_f32 v[42:43], v[42:43], v[138:139] op_sel_hi:[1,0]
	v_pk_mul_f32 v[44:45], v[44:45], v[138:139] op_sel_hi:[1,0]
	v_pk_mul_f32 v[166:167], v[46:47], v[46:47]
	v_pk_mul_f32 v[168:169], v[48:49], v[48:49]
	v_pk_mul_f32 v[170:171], v[42:43], v[42:43]
	v_pk_mul_f32 v[172:173], v[44:45], v[44:45]
	v_pk_fma_f32 v[166:167], v[144:145], v[166:167], v[146:147]
	v_pk_fma_f32 v[168:169], v[144:145], v[168:169], v[146:147]
	v_pk_fma_f32 v[170:171], v[144:145], v[170:171], v[146:147]
	v_pk_fma_f32 v[172:173], v[144:145], v[172:173], v[146:147]
	v_pk_mul_f32 v[166:167], v[46:47], v[166:167]
	v_pk_mul_f32 v[168:169], v[48:49], v[168:169]
	v_pk_mul_f32 v[170:171], v[42:43], v[170:171]
	v_pk_mul_f32 v[172:173], v[44:45], v[172:173]
	v_exp_f32_e32 v166, v166
	v_exp_f32_e32 v167, v167
	v_exp_f32_e32 v168, v168
	v_exp_f32_e32 v169, v169
	v_exp_f32_e32 v170, v170
	v_exp_f32_e32 v171, v171
	v_exp_f32_e32 v172, v172
	v_exp_f32_e32 v173, v173
	v_pk_add_f32 v[166:167], v[166:167], 1.0 op_sel_hi:[1,0]
	v_pk_add_f32 v[168:169], v[168:169], 1.0 op_sel_hi:[1,0]
	v_pk_add_f32 v[170:171], v[170:171], 1.0 op_sel_hi:[1,0]
	v_pk_add_f32 v[172:173], v[172:173], 1.0 op_sel_hi:[1,0]
	v_rcp_f32_e32 v166, v166
	v_rcp_f32_e32 v167, v167
	v_rcp_f32_e32 v168, v168
	v_rcp_f32_e32 v169, v169
	v_rcp_f32_e32 v170, v170
	v_rcp_f32_e32 v171, v171
	v_rcp_f32_e32 v172, v172
	v_rcp_f32_e32 v173, v173
	v_pk_mul_f32 v[46:47], v[46:47], v[166:167]
	v_pk_mul_f32 v[48:49], v[48:49], v[168:169]
	v_pk_mul_f32 v[42:43], v[42:43], v[170:171]
	v_pk_mul_f32 v[44:45], v[44:45], v[172:173]
	v_cvt_pk_bf16_f32 v46, v46, v47
	v_cvt_pk_bf16_f32 v47, v48, v49
; __device__ __forceinline__ u32x4 pack8(const f32x4 a, const f32x4 b) { u32x4 w; w.x = cvt_pk_bf16(a[0], a[1]); w.y = cvt_pk_bf16(a[2], a[3]); w.z = cvt_pk_bf16(b[0], b[1]); w.w = cvt_pk_bf16(b[2], b[3]); return w; }
;     __device__ __forceinline__ void operator()(const f32x4 (&acc)[2][2][4][2], const Unit& u, int wr, int wc, int fr, int fq) const {
;     ...
;                 const int row = row0 + ai * 128 + m * 16; const float rs = (u.pm == pm0) ? RS[row & 255] : row_rstd(ss, row);
; #pragma unroll
;                 for (int bj = 0; bj < 2; ++bj) {
;                     f32x4 v[2], e[2];
; #pragma unroll
;                     for (int n = 0; n < 2; ++n) { v[n] = acc[ai][bj][m][n] * rs; e[n] = v[n] * ((v[n] * v[n]) * c3 + c1); }
;                     if (kind != 0) {
; #pragma unroll
;                         for (int n = 0; n < 2; ++n)
; #pragma unroll
;                             for (int j = 0; j < 4; ++j) e[n][j] = __builtin_amdgcn_exp2f(e[n][j]);
; #pragma unroll
;                         for (int n = 0; n < 2; ++n) e[n] = e[n] + 1.0f;
; #pragma unroll
;                         for (int n = 0; n < 2; ++n)
; #pragma unroll
;                             for (int j = 0; j < 4; ++j) e[n][j] = __builtin_amdgcn_rcpf(e[n][j]);
;                         if (kind == 1) { v[0] = v[0] * e[0]; v[1] = v[1] * e[1]; } else { v[0] = e[0]; v[1] = e[1]; }
;                     }
;                     __builtin_nontemporal_store(pack8(v[0], v[1]), (u32x4*)(base + (size_t)row * ld + col0 + bj * 128));
	v_cvt_pk_bf16_f32 v48, v42, v43
	v_cvt_pk_bf16_f32 v49, v44, v45
	global_store_dwordx4 v141, v[46:49], s[56:57] sc1
	v_pk_mul_f32 v[38:39], v[38:39], v[138:139] op_sel_hi:[1,0]
	v_pk_mul_f32 v[40:41], v[40:41], v[138:139] op_sel_hi:[1,0]
	v_pk_mul_f32 v[34:35], v[34:35], v[138:139] op_sel_hi:[1,0]
	v_pk_mul_f32 v[36:37], v[36:37], v[138:139] op_sel_hi:[1,0]
	v_pk_mul_f32 v[166:167], v[38:39], v[38:39]
	v_pk_mul_f32 v[168:169], v[40:41], v[40:41]
	v_pk_mul_f32 v[170:171], v[34:35], v[34:35]
	v_pk_mul_f32 v[172:173], v[36:37], v[36:37]
	v_pk_fma_f32 v[166:167], v[144:145], v[166:167], v[146:147]
	v_pk_fma_f32 v[168:169], v[144:145], v[168:169], v[146:147]
	v_pk_fma_f32 v[170:171], v[144:145], v[170:171], v[146:147]
	v_pk_fma_f32 v[172:173], v[144:145], v[172:173], v[146:147]
	v_pk_mul_f32 v[166:167], v[38:39], v[166:167]
	v_pk_mul_f32 v[168:169], v[40:41], v[168:169]
	v_pk_mul_f32 v[170:171], v[34:35], v[170:171]
	v_pk_mul_f32 v[172:173], v[36:37], v[172:173]
	v_exp_f32_e32 v166, v166
	v_exp_f32_e32 v167, v167
	v_exp_f32_e32 v168, v168
	v_exp_f32_e32 v169, v169
	v_exp_f32_e32 v170, v170
	v_exp_f32_e32 v171, v171
	v_exp_f32_e32 v172, v172
	v_exp_f32_e32 v173, v173
	v_pk_add_f32 v[166:167], v[166:167], 1.0 op_sel_hi:[1,0]
	v_pk_add_f32 v[168:169], v[168:169], 1.0 op_sel_hi:[1,0]
	v_pk_add_f32 v[170:171], v[170:171], 1.0 op_sel_hi:[1,0]
	v_pk_add_f32 v[172:173], v[172:173], 1.0 op_sel_hi:[1,0]
	v_rcp_f32_e32 v166, v166
	v_rcp_f32_e32 v167, v167
	v_rcp_f32_e32 v168, v168
	v_rcp_f32_e32 v169, v169
	v_rcp_f32_e32 v170, v170
	v_rcp_f32_e32 v171, v171
	v_rcp_f32_e32 v172, v172
	v_rcp_f32_e32 v173, v173
	v_pk_mul_f32 v[38:39], v[38:39], v[166:167]
	v_pk_mul_f32 v[40:41], v[40:41], v[168:169]
	v_pk_mul_f32 v[34:35], v[34:35], v[170:171]
	v_pk_mul_f32 v[36:37], v[36:37], v[172:173]
	v_cvt_pk_bf16_f32 v38, v38, v39
	v_cvt_pk_bf16_f32 v39, v40, v41
	v_cvt_pk_bf16_f32 v40, v34, v35
	v_cvt_pk_bf16_f32 v41, v36, v37
	global_store_dwordx4 v141, v[38:41], s[56:57] offset:256 sc1
	s_waitcnt lgkmcnt(1)
	v_mov_b32_e32 v138, v230
	v_add_u32_e32 v141, 0x104000, v140
	v_pk_mul_f32 v[30:31], v[30:31], v[138:139] op_sel_hi:[1,0]
	v_pk_mul_f32 v[32:33], v[32:33], v[138:139] op_sel_hi:[1,0]
	v_pk_mul_f32 v[26:27], v[26:27], v[138:139] op_sel_hi:[1,0]
	v_pk_mul_f32 v[28:29], v[28:29], v[138:139] op_sel_hi:[1,0]
	v_pk_mul_f32 v[166:167], v[30:31], v[30:31]
	v_pk_mul_f32 v[168:169], v[32:33], v[32:33]
	v_pk_mul_f32 v[170:171], v[26:27], v[26:27]
	v_pk_mul_f32 v[172:173], v[28:29], v[28:29]
	v_pk_fma_f32 v[166:167], v[144:145], v[166:167], v[146:147]
	v_pk_fma_f32 v[168:169], v[144:145], v[168:169], v[146:147]
	v_pk_fma_f32 v[170:171], v[144:145], v[170:171], v[146:147]
	v_pk_fma_f32 v[172:173], v[144:145], v[172:173], v[146:147]
	v_pk_mul_f32 v[166:167], v[30:31], v[166:167]
	v_pk_mul_f32 v[168:169], v[32:33], v[168:169]
	v_pk_mul_f32 v[170:171], v[26:27], v[170:171]
	v_pk_mul_f32 v[172:173], v[28:29], v[172:173]
	v_exp_f32_e32 v166, v166
	v_exp_f32_e32 v167, v167
	v_exp_f32_e32 v168, v168
	v_exp_f32_e32 v169, v169
	v_exp_f32_e32 v170, v170
	v_exp_f32_e32 v171, v171
	v_exp_f32_e32 v172, v172
	v_exp_f32_e32 v173, v173
	v_pk_add_f32 v[166:167], v[166:167], 1.0 op_sel_hi:[1,0]
	v_pk_add_f32 v[168:169], v[168:169], 1.0 op_sel_hi:[1,0]
	v_pk_add_f32 v[170:171], v[170:171], 1.0 op_sel_hi:[1,0]
	v_pk_add_f32 v[172:173], v[172:173], 1.0 op_sel_hi:[1,0]
	v_rcp_f32_e32 v166, v166
	v_rcp_f32_e32 v167, v167
	v_rcp_f32_e32 v168, v168
	v_rcp_f32_e32 v169, v169
	v_rcp_f32_e32 v170, v170
	v_rcp_f32_e32 v171, v171
	v_rcp_f32_e32 v172, v172
	v_rcp_f32_e32 v173, v173
	v_pk_mul_f32 v[30:31], v[30:31], v[166:167]
	v_pk_mul_f32 v[32:33], v[32:33], v[168:169]
	v_pk_mul_f32 v[26:27], v[26:27], v[170:171]
	v_pk_mul_f32 v[28:29], v[28:29], v[172:173]
	v_cvt_pk_bf16_f32 v30, v30, v31
	v_cvt_pk_bf16_f32 v31, v32, v33
	v_cvt_pk_bf16_f32 v32, v26, v27
	v_cvt_pk_bf16_f32 v33, v28, v29
	global_store_dwordx4 v141, v[30:33], s[56:57] sc1
	v_pk_mul_f32 v[22:23], v[22:23], v[138:139] op_sel_hi:[1,0]
	v_pk_mul_f32 v[24:25], v[24:25], v[138:139] op_sel_hi:[1,0]
	v_pk_mul_f32 v[18:19], v[18:19], v[138:139] op_sel_hi:[1,0]
	v_pk_mul_f32 v[20:21], v[20:21], v[138:139] op_sel_hi:[1,0]
	v_pk_mul_f32 v[166:167], v[22:23], v[22:23]
	v_pk_mul_f32 v[168:169], v[24:25], v[24:25]
	v_pk_mul_f32 v[170:171], v[18:19], v[18:19]
	v_pk_mul_f32 v[172:173], v[20:21], v[20:21]
	v_pk_fma_f32 v[166:167], v[144:145], v[166:167], v[146:147]
	v_pk_fma_f32 v[168:169], v[144:145], v[168:169], v[146:147]
	v_pk_fma_f32 v[170:171], v[144:145], v[170:171], v[146:147]
	v_pk_fma_f32 v[172:173], v[144:145], v[172:173], v[146:147]
	v_pk_mul_f32 v[166:167], v[22:23], v[166:167]
	v_pk_mul_f32 v[168:169], v[24:25], v[168:169]
	v_pk_mul_f32 v[170:171], v[18:19], v[170:171]
	v_pk_mul_f32 v[172:173], v[20:21], v[172:173]
	v_exp_f32_e32 v166, v166
	v_exp_f32_e32 v167, v167
	v_exp_f32_e32 v168, v168
	v_exp_f32_e32 v169, v169
	v_exp_f32_e32 v170, v170
	v_exp_f32_e32 v171, v171
	v_exp_f32_e32 v172, v172
	v_exp_f32_e32 v173, v173
	v_pk_add_f32 v[166:167], v[166:167], 1.0 op_sel_hi:[1,0]
	v_pk_add_f32 v[168:169], v[168:169], 1.0 op_sel_hi:[1,0]
	v_pk_add_f32 v[170:171], v[170:171], 1.0 op_sel_hi:[1,0]
	v_pk_add_f32 v[172:173], v[172:173], 1.0 op_sel_hi:[1,0]
	v_rcp_f32_e32 v166, v166
	v_rcp_f32_e32 v167, v167
	v_rcp_f32_e32 v168, v168
	v_rcp_f32_e32 v169, v169
	v_rcp_f32_e32 v170, v170
	v_rcp_f32_e32 v171, v171
	v_rcp_f32_e32 v172, v172
	v_rcp_f32_e32 v173, v173
	v_pk_mul_f32 v[22:23], v[22:23], v[166:167]
	v_pk_mul_f32 v[24:25], v[24:25], v[168:169]
	v_pk_mul_f32 v[18:19], v[18:19], v[170:171]
	v_pk_mul_f32 v[20:21], v[20:21], v[172:173]
	v_cvt_pk_bf16_f32 v22, v22, v23
	v_cvt_pk_bf16_f32 v23, v24, v25
	v_cvt_pk_bf16_f32 v24, v18, v19
	v_cvt_pk_bf16_f32 v25, v20, v21
	global_store_dwordx4 v141, v[22:25], s[56:57] offset:256 sc1
	s_waitcnt lgkmcnt(0)
; __device__ __forceinline__ u32x4 pack8(const f32x4 a, const f32x4 b) { u32x4 w; w.x = cvt_pk_bf16(a[0], a[1]); w.y = cvt_pk_bf16(a[2], a[3]); w.z = cvt_pk_bf16(b[0], b[1]); w.w = cvt_pk_bf16(b[2], b[3]); return w; }
;     __device__ __forceinline__ void operator()(const f32x4 (&acc)[2][2][4][2], const Unit& u, int wr, int wc, int fr, int fq) const {
;     ...
;                 const int row = row0 + ai * 128 + m * 16; const float rs = (u.pm == pm0) ? RS[row & 255] : row_rstd(ss, row);
; #pragma unroll
;                 for (int bj = 0; bj < 2; ++bj) {
;                     f32x4 v[2], e[2];
; #pragma unroll
;                     for (int n = 0; n < 2; ++n) { v[n] = acc[ai][bj][m][n] * rs; e[n] = v[n] * ((v[n] * v[n]) * c3 + c1); }
;                     if (kind != 0) {
; #pragma unroll
;                         for (int n = 0; n < 2; ++n)
; #pragma unroll
;                             for (int j = 0; j < 4; ++j) e[n][j] = __builtin_amdgcn_exp2f(e[n][j]);
; #pragma unroll
;                         for (int n = 0; n < 2; ++n) e[n] = e[n] + 1.0f;
; #pragma unroll
;                         for (int n = 0; n < 2; ++n)
; #pragma unroll
;                             for (int j = 0; j < 4; ++j) e[n][j] = __builtin_amdgcn_rcpf(e[n][j]);
;                         if (kind == 1) { v[0] = v[0] * e[0]; v[1] = v[1] * e[1]; } else { v[0] = e[0]; v[1] = e[1]; }
;                     }
;                     __builtin_nontemporal_store(pack8(v[0], v[1]), (u32x4*)(base + (size_t)row * ld + col0 + bj * 128));
	v_mov_b32_e32 v138, v231
	v_add_u32_e32 v141, 0x11e000, v140
	v_pk_mul_f32 v[14:15], v[14:15], v[138:139] op_sel_hi:[1,0]
	v_pk_mul_f32 v[16:17], v[16:17], v[138:139] op_sel_hi:[1,0]
	v_pk_mul_f32 v[10:11], v[10:11], v[138:139] op_sel_hi:[1,0]
	v_pk_mul_f32 v[12:13], v[12:13], v[138:139] op_sel_hi:[1,0]
	v_pk_mul_f32 v[166:167], v[14:15], v[14:15]
	v_pk_mul_f32 v[168:169], v[16:17], v[16:17]
	v_pk_mul_f32 v[170:171], v[10:11], v[10:11]
	v_pk_mul_f32 v[172:173], v[12:13], v[12:13]
	v_pk_fma_f32 v[166:167], v[144:145], v[166:167], v[146:147]
	v_pk_fma_f32 v[168:169], v[144:145], v[168:169], v[146:147]
	v_pk_fma_f32 v[170:171], v[144:145], v[170:171], v[146:147]
	v_pk_fma_f32 v[172:173], v[144:145], v[172:173], v[146:147]
	v_pk_mul_f32 v[166:167], v[14:15], v[166:167]
	v_pk_mul_f32 v[168:169], v[16:17], v[168:169]
	v_pk_mul_f32 v[170:171], v[10:11], v[170:171]
	v_pk_mul_f32 v[172:173], v[12:13], v[172:173]
	v_exp_f32_e32 v166, v166
	v_exp_f32_e32 v167, v167
	v_exp_f32_e32 v168, v168
	v_exp_f32_e32 v169, v169
	v_exp_f32_e32 v170, v170
	v_exp_f32_e32 v171, v171
	v_exp_f32_e32 v172, v172
	v_exp_f32_e32 v173, v173
	v_pk_add_f32 v[166:167], v[166:167], 1.0 op_sel_hi:[1,0]
	v_pk_add_f32 v[168:169], v[168:169], 1.0 op_sel_hi:[1,0]
	v_pk_add_f32 v[170:171], v[170:171], 1.0 op_sel_hi:[1,0]
	v_pk_add_f32 v[172:173], v[172:173], 1.0 op_sel_hi:[1,0]
	v_rcp_f32_e32 v166, v166
	v_rcp_f32_e32 v167, v167
	v_rcp_f32_e32 v168, v168
	v_rcp_f32_e32 v169, v169
	v_rcp_f32_e32 v170, v170
	v_rcp_f32_e32 v171, v171
	v_rcp_f32_e32 v172, v172
	v_rcp_f32_e32 v173, v173
	v_pk_mul_f32 v[14:15], v[14:15], v[166:167]
	v_pk_mul_f32 v[16:17], v[16:17], v[168:169]
	v_pk_mul_f32 v[10:11], v[10:11], v[170:171]
	v_pk_mul_f32 v[12:13], v[12:13], v[172:173]
	v_cvt_pk_bf16_f32 v14, v14, v15
	v_cvt_pk_bf16_f32 v15, v16, v17
	v_cvt_pk_bf16_f32 v16, v10, v11
	v_cvt_pk_bf16_f32 v17, v12, v13
	global_store_dwordx4 v141, v[14:17], s[56:57] sc1
	v_pk_mul_f32 v[6:7], v[6:7], v[138:139] op_sel_hi:[1,0]
	v_pk_mul_f32 v[8:9], v[8:9], v[138:139] op_sel_hi:[1,0]
	v_pk_mul_f32 v[2:3], v[2:3], v[138:139] op_sel_hi:[1,0]
	v_pk_mul_f32 v[4:5], v[4:5], v[138:139] op_sel_hi:[1,0]
	v_pk_mul_f32 v[166:167], v[6:7], v[6:7]
	v_pk_mul_f32 v[168:169], v[8:9], v[8:9]
	v_pk_mul_f32 v[170:171], v[2:3], v[2:3]
	v_pk_mul_f32 v[172:173], v[4:5], v[4:5]
	v_pk_fma_f32 v[166:167], v[144:145], v[166:167], v[146:147]
	v_pk_fma_f32 v[168:169], v[144:145], v[168:169], v[146:147]
	v_pk_fma_f32 v[170:171], v[144:145], v[170:171], v[146:147]
	v_pk_fma_f32 v[172:173], v[144:145], v[172:173], v[146:147]
	v_pk_mul_f32 v[166:167], v[6:7], v[166:167]
	v_pk_mul_f32 v[168:169], v[8:9], v[168:169]
	v_pk_mul_f32 v[170:171], v[2:3], v[170:171]
	v_pk_mul_f32 v[172:173], v[4:5], v[172:173]
	v_exp_f32_e32 v166, v166
	v_exp_f32_e32 v167, v167
	v_exp_f32_e32 v168, v168
	v_exp_f32_e32 v169, v169
	v_exp_f32_e32 v170, v170
	v_exp_f32_e32 v171, v171
	v_exp_f32_e32 v172, v172
	v_exp_f32_e32 v173, v173
	v_pk_add_f32 v[166:167], v[166:167], 1.0 op_sel_hi:[1,0]
	v_pk_add_f32 v[168:169], v[168:169], 1.0 op_sel_hi:[1,0]
	v_pk_add_f32 v[170:171], v[170:171], 1.0 op_sel_hi:[1,0]
	v_pk_add_f32 v[172:173], v[172:173], 1.0 op_sel_hi:[1,0]
	v_rcp_f32_e32 v166, v166
	v_rcp_f32_e32 v167, v167
	v_rcp_f32_e32 v168, v168
	v_rcp_f32_e32 v169, v169
	v_rcp_f32_e32 v170, v170
	v_rcp_f32_e32 v171, v171
	v_rcp_f32_e32 v172, v172
	v_rcp_f32_e32 v173, v173
	v_pk_mul_f32 v[6:7], v[6:7], v[166:167]
	v_pk_mul_f32 v[8:9], v[8:9], v[168:169]
	v_pk_mul_f32 v[2:3], v[2:3], v[170:171]
	v_pk_mul_f32 v[4:5], v[4:5], v[172:173]
	v_cvt_pk_bf16_f32 v6, v6, v7
	v_cvt_pk_bf16_f32 v7, v8, v9
	v_cvt_pk_bf16_f32 v8, v2, v3
	v_cvt_pk_bf16_f32 v9, v4, v5
	global_store_dwordx4 v141, v[6:9], s[56:57] offset:256 sc1
	s_branch .Lpj_done
.Lpj_k0:
	s_lshl_b32 s13, s6, 8
	v_or_b32_e32 v141, s13, v163
	v_mul_u32_u24_e32 v140, 0xe00, v140
	v_lshl_add_u32 v140, v141, 1, v140
	s_waitcnt lgkmcnt(7)
	v_mov_b32_e32 v138, v224
	v_pk_mul_f32 v[126:127], v[126:127], v[138:139] op_sel_hi:[1,0]
	v_pk_mul_f32 v[128:129], v[128:129], v[138:139] op_sel_hi:[1,0]
	v_pk_mul_f32 v[122:123], v[122:123], v[138:139] op_sel_hi:[1,0]
	v_pk_mul_f32 v[124:125], v[124:125], v[138:139] op_sel_hi:[1,0]
	v_cvt_pk_bf16_f32 v126, v126, v127
	v_cvt_pk_bf16_f32 v127, v128, v129
	v_cvt_pk_bf16_f32 v128, v122, v123
	v_cvt_pk_bf16_f32 v129, v124, v125
	global_store_dwordx4 v140, v[126:129], s[36:37] sc1
	v_pk_mul_f32 v[118:119], v[118:119], v[138:139] op_sel_hi:[1,0]
	v_pk_mul_f32 v[120:121], v[120:121], v[138:139] op_sel_hi:[1,0]
	v_pk_mul_f32 v[114:115], v[114:115], v[138:139] op_sel_hi:[1,0]
	v_pk_mul_f32 v[116:117], v[116:117], v[138:139] op_sel_hi:[1,0]
	v_cvt_pk_bf16_f32 v118, v118, v119
	v_cvt_pk_bf16_f32 v119, v120, v121
	v_cvt_pk_bf16_f32 v120, v114, v115
	v_cvt_pk_bf16_f32 v121, v116, v117
	global_store_dwordx4 v140, v[118:121], s[36:37] offset:256 sc1
	s_waitcnt lgkmcnt(6)
	v_mov_b32_e32 v138, v225
	v_add_u32_e32 v141, 0xe000, v140
	v_pk_mul_f32 v[110:111], v[110:111], v[138:139] op_sel_hi:[1,0]
	v_pk_mul_f32 v[112:113], v[112:113], v[138:139] op_sel_hi:[1,0]
	v_pk_mul_f32 v[106:107], v[106:107], v[138:139] op_sel_hi:[1,0]
	v_pk_mul_f32 v[108:109], v[108:109], v[138:139] op_sel_hi:[1,0]
	v_cvt_pk_bf16_f32 v110, v110, v111
	v_cvt_pk_bf16_f32 v111, v112, v113
	v_cvt_pk_bf16_f32 v112, v106, v107
	v_cvt_pk_bf16_f32 v113, v108, v109
	global_store_dwordx4 v141, v[110:113], s[36:37] sc1
	v_pk_mul_f32 v[102:103], v[102:103], v[138:139] op_sel_hi:[1,0]
	v_pk_mul_f32 v[104:105], v[104:105], v[138:139] op_sel_hi:[1,0]
	v_pk_mul_f32 v[98:99], v[98:99], v[138:139] op_sel_hi:[1,0]
	v_pk_mul_f32 v[100:101], v[100:101], v[138:139] op_sel_hi:[1,0]
	v_cvt_pk_bf16_f32 v102, v102, v103
	v_cvt_pk_bf16_f32 v103, v104, v105
	v_cvt_pk_bf16_f32 v104, v98, v99
	v_cvt_pk_bf16_f32 v105, v100, v101
	global_store_dwordx4 v141, v[102:105], s[36:37] offset:256 sc1
	s_waitcnt lgkmcnt(5)
; __device__ __forceinline__ u32x4 pack8(const f32x4 a, const f32x4 b) { u32x4 w; w.x = cvt_pk_bf16(a[0], a[1]); w.y = cvt_pk_bf16(a[2], a[3]); w.z = cvt_pk_bf16(b[0], b[1]); w.w = cvt_pk_bf16(b[2], b[3]); return w; }
;     __device__ __forceinline__ void operator()(const f32x4 (&acc)[2][2][4][2], const Unit& u, int wr, int wc, int fr, int fq) const {
;     ...
;                 const int row = row0 + ai * 128 + m * 16; const float rs = (u.pm == pm0) ? RS[row & 255] : row_rstd(ss, row);
; #pragma unroll
;                 for (int bj = 0; bj < 2; ++bj) {
;                     f32x4 v[2], e[2];
; #pragma unroll
;                     for (int n = 0; n < 2; ++n) { v[n] = acc[ai][bj][m][n] * rs; e[n] = v[n] * ((v[n] * v[n]) * c3 + c1); }
;                     if (kind != 0) {
; #pragma unroll
;                         for (int n = 0; n < 2; ++n)
; #pragma unroll
;                             for (int j = 0; j < 4; ++j) e[n][j] = __builtin_amdgcn_exp2f(e[n][j]);
; #pragma unroll
;                         for (int n = 0; n < 2; ++n) e[n] = e[n] + 1.0f;
; #pragma unroll
;                         for (int n = 0; n < 2; ++n)
; #pragma unroll
;                             for (int j = 0; j < 4; ++j) e[n][j] = __builtin_amdgcn_rcpf(e[n][j]);
;                         if (kind == 1) { v[0] = v[0] * e[0]; v[1] = v[1] * e[1]; } else { v[0] = e[0]; v[1] = e[1]; }
;                     }
;                     __builtin_nontemporal_store(pack8(v[0], v[1]), (u32x4*)(base + (size_t)row * ld + col0 + bj * 128));
	v_mov_b32_e32 v138, v226
	v_add_u32_e32 v141, 0x1c000, v140
	v_pk_mul_f32 v[94:95], v[94:95], v[138:139] op_sel_hi:[1,0]
	v_pk_mul_f32 v[96:97], v[96:97], v[138:139] op_sel_hi:[1,0]
	v_pk_mul_f32 v[90:91], v[90:91], v[138:139] op_sel_hi:[1,0]
	v_pk_mul_f32 v[92:93], v[92:93], v[138:139] op_sel_hi:[1,0]
	v_cvt_pk_bf16_f32 v94, v94, v95
	v_cvt_pk_bf16_f32 v95, v96, v97
	v_cvt_pk_bf16_f32 v96, v90, v91
	v_cvt_pk_bf16_f32 v97, v92, v93
	global_store_dwordx4 v141, v[94:97], s[36:37] sc1
	v_pk_mul_f32 v[86:87], v[86:87], v[138:139] op_sel_hi:[1,0]
	v_pk_mul_f32 v[88:89], v[88:89], v[138:139] op_sel_hi:[1,0]
	v_pk_mul_f32 v[82:83], v[82:83], v[138:139] op_sel_hi:[1,0]
	v_pk_mul_f32 v[84:85], v[84:85], v[138:139] op_sel_hi:[1,0]
	v_cvt_pk_bf16_f32 v86, v86, v87
	v_cvt_pk_bf16_f32 v87, v88, v89
	v_cvt_pk_bf16_f32 v88, v82, v83
	v_cvt_pk_bf16_f32 v89, v84, v85
	global_store_dwordx4 v141, v[86:89], s[36:37] offset:256 sc1
	s_waitcnt lgkmcnt(4)
	v_mov_b32_e32 v138, v227
	v_add_u32_e32 v141, 0x2a000, v140
	v_pk_mul_f32 v[78:79], v[78:79], v[138:139] op_sel_hi:[1,0]
	v_pk_mul_f32 v[80:81], v[80:81], v[138:139] op_sel_hi:[1,0]
	v_pk_mul_f32 v[74:75], v[74:75], v[138:139] op_sel_hi:[1,0]
	v_pk_mul_f32 v[76:77], v[76:77], v[138:139] op_sel_hi:[1,0]
	v_cvt_pk_bf16_f32 v78, v78, v79
	v_cvt_pk_bf16_f32 v79, v80, v81
	v_cvt_pk_bf16_f32 v80, v74, v75
	v_cvt_pk_bf16_f32 v81, v76, v77
	global_store_dwordx4 v141, v[78:81], s[36:37] sc1
	v_pk_mul_f32 v[70:71], v[70:71], v[138:139] op_sel_hi:[1,0]
	v_pk_mul_f32 v[72:73], v[72:73], v[138:139] op_sel_hi:[1,0]
	v_pk_mul_f32 v[66:67], v[66:67], v[138:139] op_sel_hi:[1,0]
	v_pk_mul_f32 v[68:69], v[68:69], v[138:139] op_sel_hi:[1,0]
	v_cvt_pk_bf16_f32 v70, v70, v71
	v_cvt_pk_bf16_f32 v71, v72, v73
	v_cvt_pk_bf16_f32 v72, v66, v67
	v_cvt_pk_bf16_f32 v73, v68, v69
	global_store_dwordx4 v141, v[70:73], s[36:37] offset:256 sc1
	s_waitcnt lgkmcnt(3)
	v_mov_b32_e32 v138, v228
	v_add_u32_e32 v141, 0x70000, v140
	v_pk_mul_f32 v[62:63], v[62:63], v[138:139] op_sel_hi:[1,0]
	v_pk_mul_f32 v[64:65], v[64:65], v[138:139] op_sel_hi:[1,0]
	v_pk_mul_f32 v[58:59], v[58:59], v[138:139] op_sel_hi:[1,0]
	v_pk_mul_f32 v[60:61], v[60:61], v[138:139] op_sel_hi:[1,0]
	v_cvt_pk_bf16_f32 v62, v62, v63
	v_cvt_pk_bf16_f32 v63, v64, v65
	v_cvt_pk_bf16_f32 v64, v58, v59
	v_cvt_pk_bf16_f32 v65, v60, v61
	global_store_dwordx4 v141, v[62:65], s[36:37] sc1
	v_pk_mul_f32 v[54:55], v[54:55], v[138:139] op_sel_hi:[1,0]
	v_pk_mul_f32 v[56:57], v[56:57], v[138:139] op_sel_hi:[1,0]
	v_pk_mul_f32 v[50:51], v[50:51], v[138:139] op_sel_hi:[1,0]
	v_pk_mul_f32 v[52:53], v[52:53], v[138:139] op_sel_hi:[1,0]
	v_cvt_pk_bf16_f32 v54, v54, v55
	v_cvt_pk_bf16_f32 v55, v56, v57
	v_cvt_pk_bf16_f32 v56, v50, v51
	v_cvt_pk_bf16_f32 v57, v52, v53
	global_store_dwordx4 v141, v[54:57], s[36:37] offset:256 sc1
	s_waitcnt lgkmcnt(2)
	v_mov_b32_e32 v138, v229
	v_add_u32_e32 v141, 0x7e000, v140
	v_pk_mul_f32 v[46:47], v[46:47], v[138:139] op_sel_hi:[1,0]
	v_pk_mul_f32 v[48:49], v[48:49], v[138:139] op_sel_hi:[1,0]
	v_pk_mul_f32 v[42:43], v[42:43], v[138:139] op_sel_hi:[1,0]
	v_pk_mul_f32 v[44:45], v[44:45], v[138:139] op_sel_hi:[1,0]
	v_cvt_pk_bf16_f32 v46, v46, v47
	v_cvt_pk_bf16_f32 v47, v48, v49
	v_cvt_pk_bf16_f32 v48, v42, v43
	v_cvt_pk_bf16_f32 v49, v44, v45
	global_store_dwordx4 v141, v[46:49], s[36:37] sc1
	v_pk_mul_f32 v[38:39], v[38:39], v[138:139] op_sel_hi:[1,0]
	v_pk_mul_f32 v[40:41], v[40:41], v[138:139] op_sel_hi:[1,0]
	v_pk_mul_f32 v[34:35], v[34:35], v[138:139] op_sel_hi:[1,0]
	v_pk_mul_f32 v[36:37], v[36:37], v[138:139] op_sel_hi:[1,0]
	v_cvt_pk_bf16_f32 v38, v38, v39
	v_cvt_pk_bf16_f32 v39, v40, v41
	v_cvt_pk_bf16_f32 v40, v34, v35
	v_cvt_pk_bf16_f32 v41, v36, v37
	global_store_dwordx4 v141, v[38:41], s[36:37] offset:256 sc1
	s_waitcnt lgkmcnt(1)
	v_mov_b32_e32 v138, v230
	v_add_u32_e32 v141, 0x8c000, v140
	v_pk_mul_f32 v[30:31], v[30:31], v[138:139] op_sel_hi:[1,0]
	v_pk_mul_f32 v[32:33], v[32:33], v[138:139] op_sel_hi:[1,0]
	v_pk_mul_f32 v[26:27], v[26:27], v[138:139] op_sel_hi:[1,0]
	v_pk_mul_f32 v[28:29], v[28:29], v[138:139] op_sel_hi:[1,0]
	v_cvt_pk_bf16_f32 v30, v30, v31
	v_cvt_pk_bf16_f32 v31, v32, v33
	v_cvt_pk_bf16_f32 v32, v26, v27
	v_cvt_pk_bf16_f32 v33, v28, v29
	global_store_dwordx4 v141, v[30:33], s[36:37] sc1
	v_pk_mul_f32 v[22:23], v[22:23], v[138:139] op_sel_hi:[1,0]
	v_pk_mul_f32 v[24:25], v[24:25], v[138:139] op_sel_hi:[1,0]
	v_pk_mul_f32 v[18:19], v[18:19], v[138:139] op_sel_hi:[1,0]
	v_pk_mul_f32 v[20:21], v[20:21], v[138:139] op_sel_hi:[1,0]
	v_cvt_pk_bf16_f32 v22, v22, v23
	v_cvt_pk_bf16_f32 v23, v24, v25
	v_cvt_pk_bf16_f32 v24, v18, v19
	v_cvt_pk_bf16_f32 v25, v20, v21
	global_store_dwordx4 v141, v[22:25], s[36:37] offset:256 sc1
	s_waitcnt lgkmcnt(0)
	v_mov_b32_e32 v138, v231
	v_add_u32_e32 v141, 0x9a000, v140
	v_pk_mul_f32 v[14:15], v[14:15], v[138:139] op_sel_hi:[1,0]
	v_pk_mul_f32 v[16:17], v[16:17], v[138:139] op_sel_hi:[1,0]
	v_pk_mul_f32 v[10:11], v[10:11], v[138:139] op_sel_hi:[1,0]
	v_pk_mul_f32 v[12:13], v[12:13], v[138:139] op_sel_hi:[1,0]
	v_cvt_pk_bf16_f32 v14, v14, v15
	v_cvt_pk_bf16_f32 v15, v16, v17
	v_cvt_pk_bf16_f32 v16, v10, v11
	v_cvt_pk_bf16_f32 v17, v12, v13
	global_store_dwordx4 v141, v[14:17], s[36:37] sc1
	v_pk_mul_f32 v[6:7], v[6:7], v[138:139] op_sel_hi:[1,0]
	v_pk_mul_f32 v[8:9], v[8:9], v[138:139] op_sel_hi:[1,0]
	v_pk_mul_f32 v[2:3], v[2:3], v[138:139] op_sel_hi:[1,0]
	v_pk_mul_f32 v[4:5], v[4:5], v[138:139] op_sel_hi:[1,0]
	v_cvt_pk_bf16_f32 v6, v6, v7
	v_cvt_pk_bf16_f32 v7, v8, v9
	v_cvt_pk_bf16_f32 v8, v2, v3
	v_cvt_pk_bf16_f32 v9, v4, v5
	global_store_dwordx4 v141, v[6:9], s[36:37] offset:256 sc1
.Lpj_done:
	s_andn2_b64 vcc, exec, s[2:3]
	s_mov_b64 s[2:3], -1
	s_cbranch_vccnz .LBB0_488
	s_branch .Lpj_join

; #define PG8_BAR __builtin_amdgcn_s_barrier()
; template <class Epi, class Sched, bool ALIGN_EPI = false, bool SP2 = false>
; __device__ __forceinline__ void gemm_phase(PG8_LAS unsigned char* lds, const Gemm g, const Sched& S, const Epi& E) {
;     ...
;         cur = nxt; cA = nA; cB = nB; ++ui;
;         if constexpr (ALIGN_EPI) { if (wr == 1) PG8_BAR; }
;     }
.Lpj_join:
	s_andn2_b64 vcc, exec, s[0:1]
	s_cbranch_vccnz .LBB0_487
	s_barrier
	s_branch .LBB0_487
